# conv-FFN fix-up pass (P8) hand-written: scalar row addressing, all loads of a thread issued up front, prompt blocks only redo tokens 0,1 (epilogue now writes tokens 2..7), all 256 workgroups busy
# speedup vs baseline: 1.0107x; 1.0107x over previous
; __device__ __forceinline__ float siluf_(float x) { return x * __builtin_amdgcn_rcpf(1.f + __expf(-x)); }
; template <int NT, bool SAMPLE>
; __device__ __forceinline__ void ffn_item(const bf16_t* U, int row0, bool has_hist, const float* st, int cgi, const float* w, const float* bias, bf16_t* ACT, float* state_out) {
;     ...
;     for (int t = 0; t < NT; ++t) {
;         float cg_[8], cv_[8], o[8];
;         unpack8(rg[t], cg_); unpack8(rv[t], cv_);
; #pragma unroll
;         for (int e = 0; e < 8; ++e) {
;             const float gg = g0[e] * wg[0][e] + g1[e] * wg[1][e] + cg_[e] * wg[2][e] + bg[e];
;             const float vv = v0[e] * wv[0][e] + v1[e] * wv[1][e] + cv_[e] * wv[2][e] + bvv[e];
;             o[e] = siluf_(gg) * vv; g0[e] = g1[e]; g1[e] = cg_[e]; v0[e] = v1[e]; v1[e] = cv_[e]; }
;         *(u32x4*)(ACT + (size_t)(row0 + t) * FF + c0) = pack8(o);
.Lepi7_nostate3:
	s_waitcnt vmcnt(16)
	v_mov_b32_dpp v244, v92 row_shr:1 row_mask:0xf bank_mask:0xf
	v_mov_b32_dpp v245, v76 row_shr:1 row_mask:0xf bank_mask:0xf
	v_mov_b32_dpp v246, v84 row_shr:1 row_mask:0xf bank_mask:0xf
	v_mov_b32_dpp v247, v68 row_shr:1 row_mask:0xf bank_mask:0xf
	v_fma_f32 v248, v124, v208, v228
	v_fma_f32 v144, v116, v220, v236
	v_fma_f32 v249, v108, v208, v228
	v_fma_f32 v145, v100, v220, v236
	v_fma_f32 v250, v92, v208, v228
	v_fma_f32 v137, v84, v220, v236
	v_fma_f32 v251, v76, v208, v228
	v_fma_f32 v166, v68, v220, v236
	v_fmac_f32_e32 v248, v245, v192
	v_fmac_f32_e32 v144, v247, v200
	v_fmac_f32_e32 v249, v124, v192
	v_fmac_f32_e32 v145, v116, v200
	v_fmac_f32_e32 v250, v108, v192
	v_fmac_f32_e32 v137, v100, v200
	v_fmac_f32_e32 v251, v92, v192
	v_fmac_f32_e32 v166, v84, v200
	v_fmac_f32_e32 v248, v244, v176
	v_fmac_f32_e32 v144, v246, v184
	v_fmac_f32_e32 v249, v245, v176
	v_fmac_f32_e32 v145, v247, v184
	v_fmac_f32_e32 v250, v124, v176
	v_fmac_f32_e32 v137, v116, v184
	v_fmac_f32_e32 v251, v108, v176
	v_fmac_f32_e32 v166, v100, v184
	v_mul_f32_e32 v167, 0xbfb8aa3b, v248
	v_mul_f32_e32 v213, 0xbfb8aa3b, v249
	v_mul_f32_e32 v214, 0xbfb8aa3b, v250
	v_mul_f32_e32 v215, 0xbfb8aa3b, v251
	v_exp_f32_e32 v167, v167
	v_exp_f32_e32 v213, v213
	v_exp_f32_e32 v214, v214
	v_exp_f32_e32 v215, v215
	v_add_f32_e32 v167, 1.0, v167
	v_add_f32_e32 v213, 1.0, v213
	v_add_f32_e32 v214, 1.0, v214
	v_add_f32_e32 v215, 1.0, v215
	v_rcp_f32_e32 v167, v167
	v_rcp_f32_e32 v213, v213
	v_rcp_f32_e32 v214, v214
	v_rcp_f32_e32 v215, v215
	v_mul_f32_e32 v248, v248, v144
	v_mul_f32_e32 v249, v249, v145
	v_mul_f32_e32 v250, v250, v137
	v_mul_f32_e32 v251, v251, v166
	v_mul_f32_e32 v124, v248, v167
	v_mul_f32_e32 v108, v249, v213
	v_mul_f32_e32 v92, v250, v214
	v_mul_f32_e32 v76, v251, v215
	v_mov_b32_dpp v244, v93 row_shr:1 row_mask:0xf bank_mask:0xf
	v_mov_b32_dpp v245, v77 row_shr:1 row_mask:0xf bank_mask:0xf
	v_mov_b32_dpp v246, v85 row_shr:1 row_mask:0xf bank_mask:0xf
	v_mov_b32_dpp v247, v69 row_shr:1 row_mask:0xf bank_mask:0xf
	v_fma_f32 v248, v125, v209, v229
	v_fma_f32 v144, v117, v221, v237
	v_fma_f32 v249, v109, v209, v229
	v_fma_f32 v145, v101, v221, v237
	v_fma_f32 v250, v93, v209, v229
	v_fma_f32 v137, v85, v221, v237
	v_fma_f32 v251, v77, v209, v229
	v_fma_f32 v166, v69, v221, v237
	v_fmac_f32_e32 v248, v245, v193
	v_fmac_f32_e32 v144, v247, v201
	v_fmac_f32_e32 v249, v125, v193
	v_fmac_f32_e32 v145, v117, v201
	v_fmac_f32_e32 v250, v109, v193
	v_fmac_f32_e32 v137, v101, v201
	v_fmac_f32_e32 v251, v93, v193
	v_fmac_f32_e32 v166, v85, v201
	v_fmac_f32_e32 v248, v244, v177
	v_fmac_f32_e32 v144, v246, v185
	v_fmac_f32_e32 v249, v245, v177
	v_fmac_f32_e32 v145, v247, v185
	v_fmac_f32_e32 v250, v125, v177
	v_fmac_f32_e32 v137, v117, v185
	v_fmac_f32_e32 v251, v109, v177
	v_fmac_f32_e32 v166, v101, v185
	v_mul_f32_e32 v167, 0xbfb8aa3b, v248
	v_mul_f32_e32 v213, 0xbfb8aa3b, v249
	v_mul_f32_e32 v214, 0xbfb8aa3b, v250
	v_mul_f32_e32 v215, 0xbfb8aa3b, v251
	v_exp_f32_e32 v167, v167
	v_exp_f32_e32 v213, v213
	v_exp_f32_e32 v214, v214
	v_exp_f32_e32 v215, v215
	v_add_f32_e32 v167, 1.0, v167
	v_add_f32_e32 v213, 1.0, v213
	v_add_f32_e32 v214, 1.0, v214
	v_add_f32_e32 v215, 1.0, v215
	v_rcp_f32_e32 v167, v167
	v_rcp_f32_e32 v213, v213
	v_rcp_f32_e32 v214, v214
	v_rcp_f32_e32 v215, v215
	v_mul_f32_e32 v248, v248, v144
	v_mul_f32_e32 v249, v249, v145
	v_mul_f32_e32 v250, v250, v137
	v_mul_f32_e32 v251, v251, v166
	v_mul_f32_e32 v125, v248, v167
	v_mul_f32_e32 v109, v249, v213
	v_mul_f32_e32 v93, v250, v214
	v_mul_f32_e32 v77, v251, v215
	v_mov_b32_dpp v244, v94 row_shr:1 row_mask:0xf bank_mask:0xf
	v_mov_b32_dpp v245, v78 row_shr:1 row_mask:0xf bank_mask:0xf
	v_mov_b32_dpp v246, v86 row_shr:1 row_mask:0xf bank_mask:0xf
	v_mov_b32_dpp v247, v70 row_shr:1 row_mask:0xf bank_mask:0xf
	v_fma_f32 v248, v126, v210, v230
	v_fma_f32 v144, v118, v222, v238
	v_fma_f32 v249, v110, v210, v230
	v_fma_f32 v145, v102, v222, v238
	v_fma_f32 v250, v94, v210, v230
	v_fma_f32 v137, v86, v222, v238
	v_fma_f32 v251, v78, v210, v230
	v_fma_f32 v166, v70, v222, v238
	v_fmac_f32_e32 v248, v245, v194
	v_fmac_f32_e32 v144, v247, v202
	v_fmac_f32_e32 v249, v126, v194
	v_fmac_f32_e32 v145, v118, v202
	v_fmac_f32_e32 v250, v110, v194
	v_fmac_f32_e32 v137, v102, v202
	v_fmac_f32_e32 v251, v94, v194
	v_fmac_f32_e32 v166, v86, v202
	v_fmac_f32_e32 v248, v244, v178
	v_fmac_f32_e32 v144, v246, v186
	v_fmac_f32_e32 v249, v245, v178
	v_fmac_f32_e32 v145, v247, v186
	v_fmac_f32_e32 v250, v126, v178
	v_fmac_f32_e32 v137, v118, v186
	v_fmac_f32_e32 v251, v110, v178
	v_fmac_f32_e32 v166, v102, v186
	v_mul_f32_e32 v167, 0xbfb8aa3b, v248
	v_mul_f32_e32 v213, 0xbfb8aa3b, v249
	v_mul_f32_e32 v214, 0xbfb8aa3b, v250
	v_mul_f32_e32 v215, 0xbfb8aa3b, v251
	v_exp_f32_e32 v167, v167
	v_exp_f32_e32 v213, v213
	v_exp_f32_e32 v214, v214
	v_exp_f32_e32 v215, v215
	v_add_f32_e32 v167, 1.0, v167
	v_add_f32_e32 v213, 1.0, v213
	v_add_f32_e32 v214, 1.0, v214
	v_add_f32_e32 v215, 1.0, v215
	v_rcp_f32_e32 v167, v167
	v_rcp_f32_e32 v213, v213
	v_rcp_f32_e32 v214, v214
	v_rcp_f32_e32 v215, v215
	v_mul_f32_e32 v248, v248, v144
	v_mul_f32_e32 v249, v249, v145
	v_mul_f32_e32 v250, v250, v137
	v_mul_f32_e32 v251, v251, v166
	v_mul_f32_e32 v126, v248, v167
	v_mul_f32_e32 v110, v249, v213
	v_mul_f32_e32 v94, v250, v214
	v_mul_f32_e32 v78, v251, v215
	v_mov_b32_dpp v244, v95 row_shr:1 row_mask:0xf bank_mask:0xf
	v_mov_b32_dpp v245, v79 row_shr:1 row_mask:0xf bank_mask:0xf
	v_mov_b32_dpp v246, v87 row_shr:1 row_mask:0xf bank_mask:0xf
	v_mov_b32_dpp v247, v71 row_shr:1 row_mask:0xf bank_mask:0xf
; __device__ __forceinline__ float siluf_(float x) { return x * __builtin_amdgcn_rcpf(1.f + __expf(-x)); }
; template <int NT, bool SAMPLE>
; __device__ __forceinline__ void ffn_item(const bf16_t* U, int row0, bool has_hist, const float* st, int cgi, const float* w, const float* bias, bf16_t* ACT, float* state_out) {
;     ...
;     for (int t = 0; t < NT; ++t) {
;         float cg_[8], cv_[8], o[8];
;         unpack8(rg[t], cg_); unpack8(rv[t], cv_);
; #pragma unroll
;         for (int e = 0; e < 8; ++e) {
;             const float gg = g0[e] * wg[0][e] + g1[e] * wg[1][e] + cg_[e] * wg[2][e] + bg[e];
;             const float vv = v0[e] * wv[0][e] + v1[e] * wv[1][e] + cv_[e] * wv[2][e] + bvv[e];
;             o[e] = siluf_(gg) * vv; g0[e] = g1[e]; g1[e] = cg_[e]; v0[e] = v1[e]; v1[e] = cv_[e]; }
;         *(u32x4*)(ACT + (size_t)(row0 + t) * FF + c0) = pack8(o);
	v_fma_f32 v248, v127, v211, v231
	v_fma_f32 v144, v119, v223, v239
	v_fma_f32 v249, v111, v211, v231
	v_fma_f32 v145, v103, v223, v239
	v_fma_f32 v250, v95, v211, v231
	v_fma_f32 v137, v87, v223, v239
	v_fma_f32 v251, v79, v211, v231
	v_fma_f32 v166, v71, v223, v239
	v_fmac_f32_e32 v248, v245, v195
	v_fmac_f32_e32 v144, v247, v203
	v_fmac_f32_e32 v249, v127, v195
	v_fmac_f32_e32 v145, v119, v203
	v_fmac_f32_e32 v250, v111, v195
	v_fmac_f32_e32 v137, v103, v203
	v_fmac_f32_e32 v251, v95, v195
	v_fmac_f32_e32 v166, v87, v203
	v_fmac_f32_e32 v248, v244, v179
	v_fmac_f32_e32 v144, v246, v187
	v_fmac_f32_e32 v249, v245, v179
	v_fmac_f32_e32 v145, v247, v187
	v_fmac_f32_e32 v250, v127, v179
	v_fmac_f32_e32 v137, v119, v187
	v_fmac_f32_e32 v251, v111, v179
	v_fmac_f32_e32 v166, v103, v187
	v_mul_f32_e32 v167, 0xbfb8aa3b, v248
	v_mul_f32_e32 v213, 0xbfb8aa3b, v249
	v_mul_f32_e32 v214, 0xbfb8aa3b, v250
	v_mul_f32_e32 v215, 0xbfb8aa3b, v251
	v_exp_f32_e32 v167, v167
	v_exp_f32_e32 v213, v213
	v_exp_f32_e32 v214, v214
	v_exp_f32_e32 v215, v215
	v_add_f32_e32 v167, 1.0, v167
	v_add_f32_e32 v213, 1.0, v213
	v_add_f32_e32 v214, 1.0, v214
	v_add_f32_e32 v215, 1.0, v215
	v_rcp_f32_e32 v167, v167
	v_rcp_f32_e32 v213, v213
	v_rcp_f32_e32 v214, v214
	v_rcp_f32_e32 v215, v215
	v_mul_f32_e32 v248, v248, v144
	v_mul_f32_e32 v249, v249, v145
	v_mul_f32_e32 v250, v250, v137
	v_mul_f32_e32 v251, v251, v166
	v_mul_f32_e32 v127, v248, v167
	v_mul_f32_e32 v111, v249, v213
	v_mul_f32_e32 v95, v250, v214
	v_mul_f32_e32 v79, v251, v215
	v_mov_b32_dpp v244, v88 row_shr:1 row_mask:0xf bank_mask:0xf
	v_mov_b32_dpp v245, v72 row_shr:1 row_mask:0xf bank_mask:0xf
	v_mov_b32_dpp v246, v80 row_shr:1 row_mask:0xf bank_mask:0xf
	v_mov_b32_dpp v247, v64 row_shr:1 row_mask:0xf bank_mask:0xf
	v_fma_f32 v248, v120, v216, v232
	v_fma_f32 v144, v112, v224, v240
	v_fma_f32 v249, v104, v216, v232
	v_fma_f32 v145, v96, v224, v240
	v_fma_f32 v250, v88, v216, v232
	v_fma_f32 v137, v80, v224, v240
	v_fma_f32 v251, v72, v216, v232
	v_fma_f32 v166, v64, v224, v240
	v_fmac_f32_e32 v248, v245, v196
	v_fmac_f32_e32 v144, v247, v204
	v_fmac_f32_e32 v249, v120, v196
	v_fmac_f32_e32 v145, v112, v204
	v_fmac_f32_e32 v250, v104, v196
	v_fmac_f32_e32 v137, v96, v204
	v_fmac_f32_e32 v251, v88, v196
	v_fmac_f32_e32 v166, v80, v204
	v_fmac_f32_e32 v248, v244, v180
	v_fmac_f32_e32 v144, v246, v188
	v_fmac_f32_e32 v249, v245, v180
	v_fmac_f32_e32 v145, v247, v188
	v_fmac_f32_e32 v250, v120, v180
	v_fmac_f32_e32 v137, v112, v188
	v_fmac_f32_e32 v251, v104, v180
	v_fmac_f32_e32 v166, v96, v188
	v_mul_f32_e32 v167, 0xbfb8aa3b, v248
	v_mul_f32_e32 v213, 0xbfb8aa3b, v249
	v_mul_f32_e32 v214, 0xbfb8aa3b, v250
	v_mul_f32_e32 v215, 0xbfb8aa3b, v251
	v_exp_f32_e32 v167, v167
	v_exp_f32_e32 v213, v213
	v_exp_f32_e32 v214, v214
	v_exp_f32_e32 v215, v215
	v_add_f32_e32 v167, 1.0, v167
	v_add_f32_e32 v213, 1.0, v213
	v_add_f32_e32 v214, 1.0, v214
	v_add_f32_e32 v215, 1.0, v215
	v_rcp_f32_e32 v167, v167
	v_rcp_f32_e32 v213, v213
	v_rcp_f32_e32 v214, v214
	v_rcp_f32_e32 v215, v215
	v_mul_f32_e32 v248, v248, v144
	v_mul_f32_e32 v249, v249, v145
	v_mul_f32_e32 v250, v250, v137
	v_mul_f32_e32 v251, v251, v166
	v_mul_f32_e32 v120, v248, v167
	v_mul_f32_e32 v104, v249, v213
	v_mul_f32_e32 v88, v250, v214
	v_mul_f32_e32 v72, v251, v215
	v_mov_b32_dpp v244, v89 row_shr:1 row_mask:0xf bank_mask:0xf
	v_mov_b32_dpp v245, v73 row_shr:1 row_mask:0xf bank_mask:0xf
	v_mov_b32_dpp v246, v81 row_shr:1 row_mask:0xf bank_mask:0xf
	v_mov_b32_dpp v247, v65 row_shr:1 row_mask:0xf bank_mask:0xf
	v_fma_f32 v248, v121, v217, v233
	v_fma_f32 v144, v113, v225, v241
	v_fma_f32 v249, v105, v217, v233
	v_fma_f32 v145, v97, v225, v241
	v_fma_f32 v250, v89, v217, v233
	v_fma_f32 v137, v81, v225, v241
	v_fma_f32 v251, v73, v217, v233
	v_fma_f32 v166, v65, v225, v241
	v_fmac_f32_e32 v248, v245, v197
	v_fmac_f32_e32 v144, v247, v205
	v_fmac_f32_e32 v249, v121, v197
	v_fmac_f32_e32 v145, v113, v205
	v_fmac_f32_e32 v250, v105, v197
	v_fmac_f32_e32 v137, v97, v205
	v_fmac_f32_e32 v251, v89, v197
	v_fmac_f32_e32 v166, v81, v205
	v_fmac_f32_e32 v248, v244, v181
	v_fmac_f32_e32 v144, v246, v189
	v_fmac_f32_e32 v249, v245, v181
	v_fmac_f32_e32 v145, v247, v189
	v_fmac_f32_e32 v250, v121, v181
	v_fmac_f32_e32 v137, v113, v189
	v_fmac_f32_e32 v251, v105, v181
	v_fmac_f32_e32 v166, v97, v189
	v_mul_f32_e32 v167, 0xbfb8aa3b, v248
	v_mul_f32_e32 v213, 0xbfb8aa3b, v249
	v_mul_f32_e32 v214, 0xbfb8aa3b, v250
	v_mul_f32_e32 v215, 0xbfb8aa3b, v251
	v_exp_f32_e32 v167, v167
	v_exp_f32_e32 v213, v213
	v_exp_f32_e32 v214, v214
	v_exp_f32_e32 v215, v215
	v_add_f32_e32 v167, 1.0, v167
	v_add_f32_e32 v213, 1.0, v213
	v_add_f32_e32 v214, 1.0, v214
	v_add_f32_e32 v215, 1.0, v215
	v_rcp_f32_e32 v167, v167
	v_rcp_f32_e32 v213, v213
	v_rcp_f32_e32 v214, v214
	v_rcp_f32_e32 v215, v215
	v_mul_f32_e32 v248, v248, v144
	v_mul_f32_e32 v249, v249, v145
	v_mul_f32_e32 v250, v250, v137
	v_mul_f32_e32 v251, v251, v166
	v_mul_f32_e32 v121, v248, v167
	v_mul_f32_e32 v105, v249, v213
	v_mul_f32_e32 v89, v250, v214
	v_mul_f32_e32 v73, v251, v215
	v_mov_b32_dpp v244, v90 row_shr:1 row_mask:0xf bank_mask:0xf
	v_mov_b32_dpp v245, v74 row_shr:1 row_mask:0xf bank_mask:0xf
	v_mov_b32_dpp v246, v82 row_shr:1 row_mask:0xf bank_mask:0xf
	v_mov_b32_dpp v247, v66 row_shr:1 row_mask:0xf bank_mask:0xf
	v_fma_f32 v248, v122, v218, v234
	v_fma_f32 v144, v114, v226, v242
	v_fma_f32 v249, v106, v218, v234
	v_fma_f32 v145, v98, v226, v242
	v_fma_f32 v250, v90, v218, v234
	v_fma_f32 v137, v82, v226, v242
	v_fma_f32 v251, v74, v218, v234
	v_fma_f32 v166, v66, v226, v242
	v_fmac_f32_e32 v248, v245, v198
; __device__ __forceinline__ float siluf_(float x) { return x * __builtin_amdgcn_rcpf(1.f + __expf(-x)); }
; template <int NT, bool SAMPLE>
; __device__ __forceinline__ void ffn_item(const bf16_t* U, int row0, bool has_hist, const float* st, int cgi, const float* w, const float* bias, bf16_t* ACT, float* state_out) {
;     ...
;     for (int t = 0; t < NT; ++t) {
;         float cg_[8], cv_[8], o[8];
;         unpack8(rg[t], cg_); unpack8(rv[t], cv_);
; #pragma unroll
;         for (int e = 0; e < 8; ++e) {
;             const float gg = g0[e] * wg[0][e] + g1[e] * wg[1][e] + cg_[e] * wg[2][e] + bg[e];
;             const float vv = v0[e] * wv[0][e] + v1[e] * wv[1][e] + cv_[e] * wv[2][e] + bvv[e];
;             o[e] = siluf_(gg) * vv; g0[e] = g1[e]; g1[e] = cg_[e]; v0[e] = v1[e]; v1[e] = cv_[e]; }
;         *(u32x4*)(ACT + (size_t)(row0 + t) * FF + c0) = pack8(o);
	v_fmac_f32_e32 v144, v247, v206
	v_fmac_f32_e32 v249, v122, v198
	v_fmac_f32_e32 v145, v114, v206
	v_fmac_f32_e32 v250, v106, v198
	v_fmac_f32_e32 v137, v98, v206
	v_fmac_f32_e32 v251, v90, v198
	v_fmac_f32_e32 v166, v82, v206
	v_fmac_f32_e32 v248, v244, v182
	v_fmac_f32_e32 v144, v246, v190
	v_fmac_f32_e32 v249, v245, v182
	v_fmac_f32_e32 v145, v247, v190
	v_fmac_f32_e32 v250, v122, v182
	v_fmac_f32_e32 v137, v114, v190
	v_fmac_f32_e32 v251, v106, v182
	v_fmac_f32_e32 v166, v98, v190
	v_mul_f32_e32 v167, 0xbfb8aa3b, v248
	v_mul_f32_e32 v213, 0xbfb8aa3b, v249
	v_mul_f32_e32 v214, 0xbfb8aa3b, v250
	v_mul_f32_e32 v215, 0xbfb8aa3b, v251
	v_exp_f32_e32 v167, v167
	v_exp_f32_e32 v213, v213
	v_exp_f32_e32 v214, v214
	v_exp_f32_e32 v215, v215
	v_add_f32_e32 v167, 1.0, v167
	v_add_f32_e32 v213, 1.0, v213
	v_add_f32_e32 v214, 1.0, v214
	v_add_f32_e32 v215, 1.0, v215
	v_rcp_f32_e32 v167, v167
	v_rcp_f32_e32 v213, v213
	v_rcp_f32_e32 v214, v214
	v_rcp_f32_e32 v215, v215
	v_mul_f32_e32 v248, v248, v144
	v_mul_f32_e32 v249, v249, v145
	v_mul_f32_e32 v250, v250, v137
	v_mul_f32_e32 v251, v251, v166
	v_mul_f32_e32 v122, v248, v167
	v_mul_f32_e32 v106, v249, v213
	v_mul_f32_e32 v90, v250, v214
	v_mul_f32_e32 v74, v251, v215
	v_mov_b32_dpp v244, v91 row_shr:1 row_mask:0xf bank_mask:0xf
	v_mov_b32_dpp v245, v75 row_shr:1 row_mask:0xf bank_mask:0xf
	v_mov_b32_dpp v246, v83 row_shr:1 row_mask:0xf bank_mask:0xf
	v_mov_b32_dpp v247, v67 row_shr:1 row_mask:0xf bank_mask:0xf
	v_fma_f32 v248, v123, v219, v235
	v_fma_f32 v144, v115, v227, v243
	v_fma_f32 v249, v107, v219, v235
	v_fma_f32 v145, v99, v227, v243
	v_fma_f32 v250, v91, v219, v235
	v_fma_f32 v137, v83, v227, v243
	v_fma_f32 v251, v75, v219, v235
	v_fma_f32 v166, v67, v227, v243
	v_fmac_f32_e32 v248, v245, v199
	v_fmac_f32_e32 v144, v247, v207
	v_fmac_f32_e32 v249, v123, v199
	v_fmac_f32_e32 v145, v115, v207
	v_fmac_f32_e32 v250, v107, v199
	v_fmac_f32_e32 v137, v99, v207
	v_fmac_f32_e32 v251, v91, v199
	v_fmac_f32_e32 v166, v83, v207
	v_fmac_f32_e32 v248, v244, v183
	v_fmac_f32_e32 v144, v246, v191
	v_fmac_f32_e32 v249, v245, v183
	v_fmac_f32_e32 v145, v247, v191
	v_fmac_f32_e32 v250, v123, v183
	v_fmac_f32_e32 v137, v115, v191
	v_fmac_f32_e32 v251, v107, v183
	v_fmac_f32_e32 v166, v99, v191
	v_mul_f32_e32 v167, 0xbfb8aa3b, v248
	v_mul_f32_e32 v213, 0xbfb8aa3b, v249
	v_mul_f32_e32 v214, 0xbfb8aa3b, v250
	v_mul_f32_e32 v215, 0xbfb8aa3b, v251
	v_exp_f32_e32 v167, v167
	v_exp_f32_e32 v213, v213
	v_exp_f32_e32 v214, v214
	v_exp_f32_e32 v215, v215
	v_add_f32_e32 v167, 1.0, v167
	v_add_f32_e32 v213, 1.0, v213
	v_add_f32_e32 v214, 1.0, v214
	v_add_f32_e32 v215, 1.0, v215
	v_rcp_f32_e32 v167, v167
	v_rcp_f32_e32 v213, v213
	v_rcp_f32_e32 v214, v214
	v_rcp_f32_e32 v215, v215
	v_mul_f32_e32 v248, v248, v144
	v_mul_f32_e32 v249, v249, v145
	v_mul_f32_e32 v250, v250, v137
	v_mul_f32_e32 v251, v251, v166
	v_mul_f32_e32 v123, v248, v167
	v_mul_f32_e32 v107, v249, v213
	v_mul_f32_e32 v91, v250, v214
	v_mul_f32_e32 v75, v251, v215
	v_mov_b32_dpp v244, v28 row_shr:1 row_mask:0xf bank_mask:0xf
	v_mov_b32_dpp v245, v12 row_shr:1 row_mask:0xf bank_mask:0xf
	v_mov_b32_dpp v246, v20 row_shr:1 row_mask:0xf bank_mask:0xf
	v_mov_b32_dpp v247, v4 row_shr:1 row_mask:0xf bank_mask:0xf
	v_fma_f32 v248, v60, v208, v228
	v_fma_f32 v144, v52, v220, v236
	v_fma_f32 v249, v44, v208, v228
	v_fma_f32 v145, v36, v220, v236
	v_fma_f32 v250, v28, v208, v228
	v_fma_f32 v137, v20, v220, v236
	v_fma_f32 v251, v12, v208, v228
	v_fma_f32 v166, v4, v220, v236
	v_fmac_f32_e32 v248, v245, v192
	v_fmac_f32_e32 v144, v247, v200
	v_fmac_f32_e32 v249, v60, v192
	v_fmac_f32_e32 v145, v52, v200
	v_fmac_f32_e32 v250, v44, v192
	v_fmac_f32_e32 v137, v36, v200
	v_fmac_f32_e32 v251, v28, v192
	v_fmac_f32_e32 v166, v20, v200
	v_fmac_f32_e32 v248, v244, v176
	v_fmac_f32_e32 v144, v246, v184
	v_fmac_f32_e32 v249, v245, v176
	v_fmac_f32_e32 v145, v247, v184
	v_fmac_f32_e32 v250, v60, v176
	v_fmac_f32_e32 v137, v52, v184
	v_fmac_f32_e32 v251, v44, v176
	v_fmac_f32_e32 v166, v36, v184
	v_mul_f32_e32 v167, 0xbfb8aa3b, v248
	v_mul_f32_e32 v213, 0xbfb8aa3b, v249
	v_mul_f32_e32 v214, 0xbfb8aa3b, v250
	v_mul_f32_e32 v215, 0xbfb8aa3b, v251
	v_exp_f32_e32 v167, v167
	v_exp_f32_e32 v213, v213
	v_exp_f32_e32 v214, v214
	v_exp_f32_e32 v215, v215
	v_add_f32_e32 v167, 1.0, v167
	v_add_f32_e32 v213, 1.0, v213
	v_add_f32_e32 v214, 1.0, v214
	v_add_f32_e32 v215, 1.0, v215
	v_rcp_f32_e32 v167, v167
	v_rcp_f32_e32 v213, v213
	v_rcp_f32_e32 v214, v214
	v_rcp_f32_e32 v215, v215
	v_mul_f32_e32 v248, v248, v144
	v_mul_f32_e32 v249, v249, v145
	v_mul_f32_e32 v250, v250, v137
	v_mul_f32_e32 v251, v251, v166
	v_mul_f32_e32 v60, v248, v167
	v_mul_f32_e32 v44, v249, v213
	v_mul_f32_e32 v28, v250, v214
	v_mul_f32_e32 v12, v251, v215
	v_mov_b32_dpp v244, v29 row_shr:1 row_mask:0xf bank_mask:0xf
	v_mov_b32_dpp v245, v13 row_shr:1 row_mask:0xf bank_mask:0xf
	v_mov_b32_dpp v246, v21 row_shr:1 row_mask:0xf bank_mask:0xf
	v_mov_b32_dpp v247, v5 row_shr:1 row_mask:0xf bank_mask:0xf
	v_fma_f32 v248, v61, v209, v229
	v_fma_f32 v144, v53, v221, v237
	v_fma_f32 v249, v45, v209, v229
	v_fma_f32 v145, v37, v221, v237
	v_fma_f32 v250, v29, v209, v229
	v_fma_f32 v137, v21, v221, v237
	v_fma_f32 v251, v13, v209, v229
	v_fma_f32 v166, v5, v221, v237
	v_fmac_f32_e32 v248, v245, v193
	v_fmac_f32_e32 v144, v247, v201
	v_fmac_f32_e32 v249, v61, v193
	v_fmac_f32_e32 v145, v53, v201
	v_fmac_f32_e32 v250, v45, v193
	v_fmac_f32_e32 v137, v37, v201
	v_fmac_f32_e32 v251, v29, v193
	v_fmac_f32_e32 v166, v21, v201
	v_fmac_f32_e32 v248, v244, v177
	v_fmac_f32_e32 v144, v246, v185
	v_fmac_f32_e32 v249, v245, v177
; __device__ __forceinline__ float siluf_(float x) { return x * __builtin_amdgcn_rcpf(1.f + __expf(-x)); }
; template <int NT, bool SAMPLE>
; __device__ __forceinline__ void ffn_item(const bf16_t* U, int row0, bool has_hist, const float* st, int cgi, const float* w, const float* bias, bf16_t* ACT, float* state_out) {
;     ...
;     for (int t = 0; t < NT; ++t) {
;         float cg_[8], cv_[8], o[8];
;         unpack8(rg[t], cg_); unpack8(rv[t], cv_);
; #pragma unroll
;         for (int e = 0; e < 8; ++e) {
;             const float gg = g0[e] * wg[0][e] + g1[e] * wg[1][e] + cg_[e] * wg[2][e] + bg[e];
;             const float vv = v0[e] * wv[0][e] + v1[e] * wv[1][e] + cv_[e] * wv[2][e] + bvv[e];
;             o[e] = siluf_(gg) * vv; g0[e] = g1[e]; g1[e] = cg_[e]; v0[e] = v1[e]; v1[e] = cv_[e]; }
;         *(u32x4*)(ACT + (size_t)(row0 + t) * FF + c0) = pack8(o);
	v_fmac_f32_e32 v145, v247, v185
	v_fmac_f32_e32 v250, v61, v177
	v_fmac_f32_e32 v137, v53, v185
	v_fmac_f32_e32 v251, v45, v177
	v_fmac_f32_e32 v166, v37, v185
	v_mul_f32_e32 v167, 0xbfb8aa3b, v248
	v_mul_f32_e32 v213, 0xbfb8aa3b, v249
	v_mul_f32_e32 v214, 0xbfb8aa3b, v250
	v_mul_f32_e32 v215, 0xbfb8aa3b, v251
	v_exp_f32_e32 v167, v167
	v_exp_f32_e32 v213, v213
	v_exp_f32_e32 v214, v214
	v_exp_f32_e32 v215, v215
	v_add_f32_e32 v167, 1.0, v167
	v_add_f32_e32 v213, 1.0, v213
	v_add_f32_e32 v214, 1.0, v214
	v_add_f32_e32 v215, 1.0, v215
	v_rcp_f32_e32 v167, v167
	v_rcp_f32_e32 v213, v213
	v_rcp_f32_e32 v214, v214
	v_rcp_f32_e32 v215, v215
	v_mul_f32_e32 v248, v248, v144
	v_mul_f32_e32 v249, v249, v145
	v_mul_f32_e32 v250, v250, v137
	v_mul_f32_e32 v251, v251, v166
	v_mul_f32_e32 v61, v248, v167
	v_mul_f32_e32 v45, v249, v213
	v_mul_f32_e32 v29, v250, v214
	v_mul_f32_e32 v13, v251, v215
	v_mov_b32_dpp v244, v30 row_shr:1 row_mask:0xf bank_mask:0xf
	v_mov_b32_dpp v245, v14 row_shr:1 row_mask:0xf bank_mask:0xf
	v_mov_b32_dpp v246, v22 row_shr:1 row_mask:0xf bank_mask:0xf
	v_mov_b32_dpp v247, v6 row_shr:1 row_mask:0xf bank_mask:0xf
	v_fma_f32 v248, v62, v210, v230
	v_fma_f32 v144, v54, v222, v238
	v_fma_f32 v249, v46, v210, v230
	v_fma_f32 v145, v38, v222, v238
	v_fma_f32 v250, v30, v210, v230
	v_fma_f32 v137, v22, v222, v238
	v_fma_f32 v251, v14, v210, v230
	v_fma_f32 v166, v6, v222, v238
	v_fmac_f32_e32 v248, v245, v194
	v_fmac_f32_e32 v144, v247, v202
	v_fmac_f32_e32 v249, v62, v194
	v_fmac_f32_e32 v145, v54, v202
	v_fmac_f32_e32 v250, v46, v194
	v_fmac_f32_e32 v137, v38, v202
	v_fmac_f32_e32 v251, v30, v194
	v_fmac_f32_e32 v166, v22, v202
	v_fmac_f32_e32 v248, v244, v178
	v_fmac_f32_e32 v144, v246, v186
	v_fmac_f32_e32 v249, v245, v178
	v_fmac_f32_e32 v145, v247, v186
	v_fmac_f32_e32 v250, v62, v178
	v_fmac_f32_e32 v137, v54, v186
	v_fmac_f32_e32 v251, v46, v178
	v_fmac_f32_e32 v166, v38, v186
	v_mul_f32_e32 v167, 0xbfb8aa3b, v248
	v_mul_f32_e32 v213, 0xbfb8aa3b, v249
	v_mul_f32_e32 v214, 0xbfb8aa3b, v250
	v_mul_f32_e32 v215, 0xbfb8aa3b, v251
	v_exp_f32_e32 v167, v167
	v_exp_f32_e32 v213, v213
	v_exp_f32_e32 v214, v214
	v_exp_f32_e32 v215, v215
	v_add_f32_e32 v167, 1.0, v167
	v_add_f32_e32 v213, 1.0, v213
	v_add_f32_e32 v214, 1.0, v214
	v_add_f32_e32 v215, 1.0, v215
	v_rcp_f32_e32 v167, v167
	v_rcp_f32_e32 v213, v213
	v_rcp_f32_e32 v214, v214
	v_rcp_f32_e32 v215, v215
	v_mul_f32_e32 v248, v248, v144
	v_mul_f32_e32 v249, v249, v145
	v_mul_f32_e32 v250, v250, v137
	v_mul_f32_e32 v251, v251, v166
	v_mul_f32_e32 v62, v248, v167
	v_mul_f32_e32 v46, v249, v213
	v_mul_f32_e32 v30, v250, v214
	v_mul_f32_e32 v14, v251, v215
	v_mov_b32_dpp v244, v31 row_shr:1 row_mask:0xf bank_mask:0xf
	v_mov_b32_dpp v245, v15 row_shr:1 row_mask:0xf bank_mask:0xf
	v_mov_b32_dpp v246, v23 row_shr:1 row_mask:0xf bank_mask:0xf
	v_mov_b32_dpp v247, v7 row_shr:1 row_mask:0xf bank_mask:0xf
	v_fma_f32 v248, v63, v211, v231
	v_fma_f32 v144, v55, v223, v239
	v_fma_f32 v249, v47, v211, v231
	v_fma_f32 v145, v39, v223, v239
	v_fma_f32 v250, v31, v211, v231
	v_fma_f32 v137, v23, v223, v239
	v_fma_f32 v251, v15, v211, v231
	v_fma_f32 v166, v7, v223, v239
	v_fmac_f32_e32 v248, v245, v195
	v_fmac_f32_e32 v144, v247, v203
	v_fmac_f32_e32 v249, v63, v195
	v_fmac_f32_e32 v145, v55, v203
	v_fmac_f32_e32 v250, v47, v195
	v_fmac_f32_e32 v137, v39, v203
	v_fmac_f32_e32 v251, v31, v195
	v_fmac_f32_e32 v166, v23, v203
	v_fmac_f32_e32 v248, v244, v179
	v_fmac_f32_e32 v144, v246, v187
	v_fmac_f32_e32 v249, v245, v179
	v_fmac_f32_e32 v145, v247, v187
	v_fmac_f32_e32 v250, v63, v179
	v_fmac_f32_e32 v137, v55, v187
	v_fmac_f32_e32 v251, v47, v179
	v_fmac_f32_e32 v166, v39, v187
	v_mul_f32_e32 v167, 0xbfb8aa3b, v248
	v_mul_f32_e32 v213, 0xbfb8aa3b, v249
	v_mul_f32_e32 v214, 0xbfb8aa3b, v250
	v_mul_f32_e32 v215, 0xbfb8aa3b, v251
	v_exp_f32_e32 v167, v167
	v_exp_f32_e32 v213, v213
	v_exp_f32_e32 v214, v214
	v_exp_f32_e32 v215, v215
	v_add_f32_e32 v167, 1.0, v167
	v_add_f32_e32 v213, 1.0, v213
	v_add_f32_e32 v214, 1.0, v214
	v_add_f32_e32 v215, 1.0, v215
	v_rcp_f32_e32 v167, v167
	v_rcp_f32_e32 v213, v213
	v_rcp_f32_e32 v214, v214
	v_rcp_f32_e32 v215, v215
	v_mul_f32_e32 v248, v248, v144
	v_mul_f32_e32 v249, v249, v145
	v_mul_f32_e32 v250, v250, v137
	v_mul_f32_e32 v251, v251, v166
	v_mul_f32_e32 v63, v248, v167
	v_mul_f32_e32 v47, v249, v213
	v_mul_f32_e32 v31, v250, v214
	v_mul_f32_e32 v15, v251, v215
	v_mov_b32_dpp v244, v24 row_shr:1 row_mask:0xf bank_mask:0xf
	v_mov_b32_dpp v245, v8 row_shr:1 row_mask:0xf bank_mask:0xf
	v_mov_b32_dpp v246, v16 row_shr:1 row_mask:0xf bank_mask:0xf
	v_mov_b32_dpp v247, v0 row_shr:1 row_mask:0xf bank_mask:0xf
	v_fma_f32 v248, v56, v216, v232
	v_fma_f32 v144, v48, v224, v240
	v_fma_f32 v249, v40, v216, v232
	v_fma_f32 v145, v32, v224, v240
	v_fma_f32 v250, v24, v216, v232
	v_fma_f32 v137, v16, v224, v240
	v_fma_f32 v251, v8, v216, v232
	v_fma_f32 v166, v0, v224, v240
	v_fmac_f32_e32 v248, v245, v196
	v_fmac_f32_e32 v144, v247, v204
	v_fmac_f32_e32 v249, v56, v196
	v_fmac_f32_e32 v145, v48, v204
	v_fmac_f32_e32 v250, v40, v196
	v_fmac_f32_e32 v137, v32, v204
	v_fmac_f32_e32 v251, v24, v196
	v_fmac_f32_e32 v166, v16, v204
	v_fmac_f32_e32 v248, v244, v180
	v_fmac_f32_e32 v144, v246, v188
	v_fmac_f32_e32 v249, v245, v180
	v_fmac_f32_e32 v145, v247, v188
	v_fmac_f32_e32 v250, v56, v180
	v_fmac_f32_e32 v137, v48, v188
	v_fmac_f32_e32 v251, v40, v180
	v_fmac_f32_e32 v166, v32, v188
	v_mul_f32_e32 v167, 0xbfb8aa3b, v248
	v_mul_f32_e32 v213, 0xbfb8aa3b, v249
	v_mul_f32_e32 v214, 0xbfb8aa3b, v250
	v_mul_f32_e32 v215, 0xbfb8aa3b, v251
	v_exp_f32_e32 v167, v167
; __device__ __forceinline__ float siluf_(float x) { return x * __builtin_amdgcn_rcpf(1.f + __expf(-x)); }
; template <int NT, bool SAMPLE>
; __device__ __forceinline__ void ffn_item(const bf16_t* U, int row0, bool has_hist, const float* st, int cgi, const float* w, const float* bias, bf16_t* ACT, float* state_out) {
;     ...
;     for (int t = 0; t < NT; ++t) {
;         float cg_[8], cv_[8], o[8];
;         unpack8(rg[t], cg_); unpack8(rv[t], cv_);
; #pragma unroll
;         for (int e = 0; e < 8; ++e) {
;             const float gg = g0[e] * wg[0][e] + g1[e] * wg[1][e] + cg_[e] * wg[2][e] + bg[e];
;             const float vv = v0[e] * wv[0][e] + v1[e] * wv[1][e] + cv_[e] * wv[2][e] + bvv[e];
;             o[e] = siluf_(gg) * vv; g0[e] = g1[e]; g1[e] = cg_[e]; v0[e] = v1[e]; v1[e] = cv_[e]; }
;         *(u32x4*)(ACT + (size_t)(row0 + t) * FF + c0) = pack8(o);
	v_exp_f32_e32 v213, v213
	v_exp_f32_e32 v214, v214
	v_exp_f32_e32 v215, v215
	v_add_f32_e32 v167, 1.0, v167
	v_add_f32_e32 v213, 1.0, v213
	v_add_f32_e32 v214, 1.0, v214
	v_add_f32_e32 v215, 1.0, v215
	v_rcp_f32_e32 v167, v167
	v_rcp_f32_e32 v213, v213
	v_rcp_f32_e32 v214, v214
	v_rcp_f32_e32 v215, v215
	v_mul_f32_e32 v248, v248, v144
	v_mul_f32_e32 v249, v249, v145
	v_mul_f32_e32 v250, v250, v137
	v_mul_f32_e32 v251, v251, v166
	v_mul_f32_e32 v56, v248, v167
	v_mul_f32_e32 v40, v249, v213
	v_mul_f32_e32 v24, v250, v214
	v_mul_f32_e32 v8, v251, v215
	v_mov_b32_dpp v244, v25 row_shr:1 row_mask:0xf bank_mask:0xf
	v_mov_b32_dpp v245, v9 row_shr:1 row_mask:0xf bank_mask:0xf
	v_mov_b32_dpp v246, v17 row_shr:1 row_mask:0xf bank_mask:0xf
	v_mov_b32_dpp v247, v1 row_shr:1 row_mask:0xf bank_mask:0xf
	v_fma_f32 v248, v57, v217, v233
	v_fma_f32 v144, v49, v225, v241
	v_fma_f32 v249, v41, v217, v233
	v_fma_f32 v145, v33, v225, v241
	v_fma_f32 v250, v25, v217, v233
	v_fma_f32 v137, v17, v225, v241
	v_fma_f32 v251, v9, v217, v233
	v_fma_f32 v166, v1, v225, v241
	v_fmac_f32_e32 v248, v245, v197
	v_fmac_f32_e32 v144, v247, v205
	v_fmac_f32_e32 v249, v57, v197
	v_fmac_f32_e32 v145, v49, v205
	v_fmac_f32_e32 v250, v41, v197
	v_fmac_f32_e32 v137, v33, v205
	v_fmac_f32_e32 v251, v25, v197
	v_fmac_f32_e32 v166, v17, v205
	v_fmac_f32_e32 v248, v244, v181
	v_fmac_f32_e32 v144, v246, v189
	v_fmac_f32_e32 v249, v245, v181
	v_fmac_f32_e32 v145, v247, v189
	v_fmac_f32_e32 v250, v57, v181
	v_fmac_f32_e32 v137, v49, v189
	v_fmac_f32_e32 v251, v41, v181
	v_fmac_f32_e32 v166, v33, v189
	v_mul_f32_e32 v167, 0xbfb8aa3b, v248
	v_mul_f32_e32 v213, 0xbfb8aa3b, v249
	v_mul_f32_e32 v214, 0xbfb8aa3b, v250
	v_mul_f32_e32 v215, 0xbfb8aa3b, v251
	v_exp_f32_e32 v167, v167
	v_exp_f32_e32 v213, v213
	v_exp_f32_e32 v214, v214
	v_exp_f32_e32 v215, v215
	v_add_f32_e32 v167, 1.0, v167
	v_add_f32_e32 v213, 1.0, v213
	v_add_f32_e32 v214, 1.0, v214
	v_add_f32_e32 v215, 1.0, v215
	v_rcp_f32_e32 v167, v167
	v_rcp_f32_e32 v213, v213
	v_rcp_f32_e32 v214, v214
	v_rcp_f32_e32 v215, v215
	v_mul_f32_e32 v248, v248, v144
	v_mul_f32_e32 v249, v249, v145
	v_mul_f32_e32 v250, v250, v137
	v_mul_f32_e32 v251, v251, v166
	v_mul_f32_e32 v57, v248, v167
	v_mul_f32_e32 v41, v249, v213
	v_mul_f32_e32 v25, v250, v214
	v_mul_f32_e32 v9, v251, v215
	v_mov_b32_dpp v244, v26 row_shr:1 row_mask:0xf bank_mask:0xf
	v_mov_b32_dpp v245, v10 row_shr:1 row_mask:0xf bank_mask:0xf
	v_mov_b32_dpp v246, v18 row_shr:1 row_mask:0xf bank_mask:0xf
	v_mov_b32_dpp v247, v2 row_shr:1 row_mask:0xf bank_mask:0xf
	v_fma_f32 v248, v58, v218, v234
	v_fma_f32 v144, v50, v226, v242
	v_fma_f32 v249, v42, v218, v234
	v_fma_f32 v145, v34, v226, v242
	v_fma_f32 v250, v26, v218, v234
	v_fma_f32 v137, v18, v226, v242
	v_fma_f32 v251, v10, v218, v234
	v_fma_f32 v166, v2, v226, v242
	v_fmac_f32_e32 v248, v245, v198
	v_fmac_f32_e32 v144, v247, v206
	v_fmac_f32_e32 v249, v58, v198
	v_fmac_f32_e32 v145, v50, v206
	v_fmac_f32_e32 v250, v42, v198
	v_fmac_f32_e32 v137, v34, v206
	v_fmac_f32_e32 v251, v26, v198
	v_fmac_f32_e32 v166, v18, v206
	v_fmac_f32_e32 v248, v244, v182
	v_fmac_f32_e32 v144, v246, v190
	v_fmac_f32_e32 v249, v245, v182
	v_fmac_f32_e32 v145, v247, v190
	v_fmac_f32_e32 v250, v58, v182
	v_fmac_f32_e32 v137, v50, v190
	v_fmac_f32_e32 v251, v42, v182
	v_fmac_f32_e32 v166, v34, v190
	v_mul_f32_e32 v167, 0xbfb8aa3b, v248
	v_mul_f32_e32 v213, 0xbfb8aa3b, v249
	v_mul_f32_e32 v214, 0xbfb8aa3b, v250
	v_mul_f32_e32 v215, 0xbfb8aa3b, v251
	v_exp_f32_e32 v167, v167
	v_exp_f32_e32 v213, v213
	v_exp_f32_e32 v214, v214
	v_exp_f32_e32 v215, v215
	v_add_f32_e32 v167, 1.0, v167
	v_add_f32_e32 v213, 1.0, v213
	v_add_f32_e32 v214, 1.0, v214
	v_add_f32_e32 v215, 1.0, v215
	v_rcp_f32_e32 v167, v167
	v_rcp_f32_e32 v213, v213
	v_rcp_f32_e32 v214, v214
	v_rcp_f32_e32 v215, v215
	v_mul_f32_e32 v248, v248, v144
	v_mul_f32_e32 v249, v249, v145
	v_mul_f32_e32 v250, v250, v137
	v_mul_f32_e32 v251, v251, v166
	v_mul_f32_e32 v58, v248, v167
; __device__ __forceinline__ float siluf_(float x) { return x * __builtin_amdgcn_rcpf(1.f + __expf(-x)); }
; template <int NT, bool SAMPLE>
; __device__ __forceinline__ void ffn_item(const bf16_t* U, int row0, bool has_hist, const float* st, int cgi, const float* w, const float* bias, bf16_t* ACT, float* state_out) {
;     ...
;     for (int t = 0; t < NT; ++t) {
;         float cg_[8], cv_[8], o[8];
;         unpack8(rg[t], cg_); unpack8(rv[t], cv_);
; #pragma unroll
;         for (int e = 0; e < 8; ++e) {
;             const float gg = g0[e] * wg[0][e] + g1[e] * wg[1][e] + cg_[e] * wg[2][e] + bg[e];
;             const float vv = v0[e] * wv[0][e] + v1[e] * wv[1][e] + cv_[e] * wv[2][e] + bvv[e];
;             o[e] = siluf_(gg) * vv; g0[e] = g1[e]; g1[e] = cg_[e]; v0[e] = v1[e]; v1[e] = cv_[e]; }
;         *(u32x4*)(ACT + (size_t)(row0 + t) * FF + c0) = pack8(o);
	v_mul_f32_e32 v42, v249, v213
	v_mul_f32_e32 v26, v250, v214
	v_mul_f32_e32 v10, v251, v215
	v_mov_b32_dpp v244, v27 row_shr:1 row_mask:0xf bank_mask:0xf
	v_mov_b32_dpp v245, v11 row_shr:1 row_mask:0xf bank_mask:0xf
	v_mov_b32_dpp v246, v19 row_shr:1 row_mask:0xf bank_mask:0xf
	v_mov_b32_dpp v247, v3 row_shr:1 row_mask:0xf bank_mask:0xf
	v_fma_f32 v248, v59, v219, v235
	v_fma_f32 v144, v51, v227, v243
	v_fma_f32 v249, v43, v219, v235
	v_fma_f32 v145, v35, v227, v243
	v_fma_f32 v250, v27, v219, v235
	v_fma_f32 v137, v19, v227, v243
	v_fma_f32 v251, v11, v219, v235
	v_fma_f32 v166, v3, v227, v243
	v_fmac_f32_e32 v248, v245, v199
	v_fmac_f32_e32 v144, v247, v207
	v_fmac_f32_e32 v249, v59, v199
	v_fmac_f32_e32 v145, v51, v207
	v_fmac_f32_e32 v250, v43, v199
	v_fmac_f32_e32 v137, v35, v207
	v_fmac_f32_e32 v251, v27, v199
	v_fmac_f32_e32 v166, v19, v207
	v_fmac_f32_e32 v248, v244, v183
	v_fmac_f32_e32 v144, v246, v191
	v_fmac_f32_e32 v249, v245, v183
	v_fmac_f32_e32 v145, v247, v191
	v_fmac_f32_e32 v250, v59, v183
	v_fmac_f32_e32 v137, v51, v191
	v_fmac_f32_e32 v251, v43, v183
	v_fmac_f32_e32 v166, v35, v191
	v_mul_f32_e32 v167, 0xbfb8aa3b, v248
	v_mul_f32_e32 v213, 0xbfb8aa3b, v249
	v_mul_f32_e32 v214, 0xbfb8aa3b, v250
	v_mul_f32_e32 v215, 0xbfb8aa3b, v251
	v_exp_f32_e32 v167, v167
	v_exp_f32_e32 v213, v213
	v_exp_f32_e32 v214, v214
	v_exp_f32_e32 v215, v215
	v_add_f32_e32 v167, 1.0, v167
	v_add_f32_e32 v213, 1.0, v213
	v_add_f32_e32 v214, 1.0, v214
	v_add_f32_e32 v215, 1.0, v215
	v_rcp_f32_e32 v167, v167
	v_rcp_f32_e32 v213, v213
	v_rcp_f32_e32 v214, v214
	v_rcp_f32_e32 v215, v215
	v_mul_f32_e32 v248, v248, v144
	v_mul_f32_e32 v249, v249, v145
	v_mul_f32_e32 v250, v250, v137
	v_mul_f32_e32 v251, v251, v166
	v_mul_f32_e32 v59, v248, v167
	v_mul_f32_e32 v43, v249, v213
	v_mul_f32_e32 v27, v250, v214
	v_mul_f32_e32 v11, v251, v215
	s_mov_b32 exec_lo, 0xfffefffe
	s_mov_b32 exec_hi, 0xfffefffe
	v_cvt_pk_bf16_f32 v168, v124, v125
	v_cvt_pk_bf16_f32 v169, v126, v127
	v_cvt_pk_bf16_f32 v170, v120, v121
	v_cvt_pk_bf16_f32 v171, v122, v123
	global_store_dwordx4 v136, v[168:171], s[14:15]
	s_add_u32 s14, s14, 0x2b00
	s_addc_u32 s15, s15, 0
	v_cvt_pk_bf16_f32 v172, v108, v109
	v_cvt_pk_bf16_f32 v173, v110, v111
	v_cvt_pk_bf16_f32 v174, v104, v105
	v_cvt_pk_bf16_f32 v175, v106, v107
	global_store_dwordx4 v136, v[172:175], s[14:15]
	s_add_u32 s14, s14, 0x2b00
	s_addc_u32 s15, s15, 0
	s_mov_b32 exec_lo, -1
	s_mov_b32 exec_hi, -1
	v_cvt_pk_bf16_f32 v168, v92, v93
	v_cvt_pk_bf16_f32 v169, v94, v95
	v_cvt_pk_bf16_f32 v170, v88, v89
	v_cvt_pk_bf16_f32 v171, v90, v91
	global_store_dwordx4 v136, v[168:171], s[14:15]
	s_add_u32 s14, s14, 0x2b00
	s_addc_u32 s15, s15, 0
	v_cvt_pk_bf16_f32 v172, v76, v77
	v_cvt_pk_bf16_f32 v173, v78, v79
	v_cvt_pk_bf16_f32 v174, v72, v73
	v_cvt_pk_bf16_f32 v175, v74, v75
	global_store_dwordx4 v136, v[172:175], s[14:15]
	s_add_u32 s14, s14, 0x14ff00
	s_addc_u32 s15, s15, 0
	s_mov_b32 exec_lo, 0xfffefffe
	s_mov_b32 exec_hi, 0xfffefffe
	v_cvt_pk_bf16_f32 v168, v60, v61
	v_cvt_pk_bf16_f32 v169, v62, v63
	v_cvt_pk_bf16_f32 v170, v56, v57
	v_cvt_pk_bf16_f32 v171, v58, v59
	global_store_dwordx4 v136, v[168:171], s[14:15]
	s_add_u32 s14, s14, 0x2b00
	s_addc_u32 s15, s15, 0
	v_cvt_pk_bf16_f32 v172, v44, v45
	v_cvt_pk_bf16_f32 v173, v46, v47
	v_cvt_pk_bf16_f32 v174, v40, v41
	v_cvt_pk_bf16_f32 v175, v42, v43
	global_store_dwordx4 v136, v[172:175], s[14:15]
	s_add_u32 s14, s14, 0x2b00
	s_addc_u32 s15, s15, 0
	s_mov_b32 exec_lo, -1
	s_mov_b32 exec_hi, -1
	v_cvt_pk_bf16_f32 v168, v28, v29
	v_cvt_pk_bf16_f32 v169, v30, v31
	v_cvt_pk_bf16_f32 v170, v24, v25
	v_cvt_pk_bf16_f32 v171, v26, v27
	global_store_dwordx4 v136, v[168:171], s[14:15]
	s_add_u32 s14, s14, 0x2b00
	s_addc_u32 s15, s15, 0
	v_cvt_pk_bf16_f32 v172, v12, v13
	v_cvt_pk_bf16_f32 v173, v14, v15
	v_cvt_pk_bf16_f32 v174, v8, v9
	v_cvt_pk_bf16_f32 v175, v10, v11
	global_store_dwordx4 v136, v[172:175], s[14:15]
	s_mov_b64 exec, -1
	s_branch .Lepi7_done

; #define LD8(dst, ptr) do { const f32x4 a_ = *(const f32x4*)(ptr), b_ = *(const f32x4*)((ptr) + 4); dst[0] = a_.x; dst[1] = a_.y; dst[2] = a_.z; dst[3] = a_.w; dst[4] = b_.x; dst[5] = b_.y; dst[6] = b_.z; dst[7] = b_.w; } while (0)
; template <int NT, bool SAMPLE>
; __device__ __forceinline__ void ffn_item(const bf16_t* U, int row0, bool has_hist, const float* st, int cgi, const float* w, const float* bias, bf16_t* ACT, float* state_out) {
;     const int c0 = cgi * 8;
;     float wg[3][8], wv[3][8], bg[8], bvv[8], g0[8], g1[8], v0[8], v1[8];
;     ...
; #pragma unroll
;     for (int i = 0; i < 3; ++i) { LD8(wg[i], w + i * FF2 + c0); LD8(wv[i], w + i * FF2 + FF + c0); }
;     LD8(bg, bias + c0); LD8(bvv, bias + FF + c0);
;     if (SAMPLE) {
;         LD8(g0, st + 0 * FF2 + c0); LD8(g1, st + 1 * FF2 + c0); LD8(v0, st + 0 * FF2 + FF + c0); LD8(v1, st + 1 * FF2 + FF + c0);
;     } else if (has_hist) {
;         unpack8(*(const u32x4*)(U + (size_t)(row0 - 2) * FF2 + c0), g0); unpack8(*(const u32x4*)(U + (size_t)(row0 - 1) * FF2 + c0), g1);
;         unpack8(*(const u32x4*)(U + (size_t)(row0 - 2) * FF2 + FF + c0), v0); unpack8(*(const u32x4*)(U + (size_t)(row0 - 1) * FF2 + FF + c0), v1);
;     } else {
; #pragma unroll
;         for (int e = 0; e < 8; ++e) { g0[e] = 0.f; g1[e] = 0.f; v0[e] = 0.f; v1[e] = 0.f; }
;     }
;     ...
;     u32x4 rg[NT], rv[NT];
; #pragma unroll
;     for (int t = 0; t < NT; ++t) { rg[t] = *(const u32x4*)(U + (size_t)(row0 + t) * FF2 + c0); rv[t] = *(const u32x4*)(U + (size_t)(row0 + t) * FF2 + FF + c0); }
; __global__ void __launch_bounds__(512, 2) mk_fwd(Args args) {
;     ...
;         for (int it = gt; it < DB * 688; it += NGT) { const int cgi = it % 688, s = it / 688;
;             ffn_item<4, true>(U, MP + 4 * s, true, state_ffc + (size_t)s * 2 * FF2, cgi, ffn_conv_w, ffn_conv_b, ACT, out + O_SFFC + (size_t)s * 2 * FF2); }
.LBB0_876:
	s_cmp_lt_i32 s88, 9
	s_cselect_b64 s[0:1], -1, 0
	s_and_b64 s[0:1], s[0:1], s[4:5]
	s_andn2_b64 vcc, exec, s[0:1]
	s_cbranch_vccnz .LBB0_890
	s_waitcnt vmcnt(0)
	v_readlane_b32 s3, v253, 2
	s_load_dwordx4 s[12:15], s[96:97], 0xc8
	s_load_dwordx2 s[20:21], s[96:97], 0x28
	s_load_dwordx4 s[16:19], s[96:97], 0xa8
	v_cmp_gt_u32_e32 vcc, 344, v212
	s_and_saveexec_b64 s[10:11], vcc
	s_cbranch_execz .Lp8_end
	s_lshr_b32 s33, s3, 1
	s_and_b32 s4, s3, 1
	s_mul_i32 s4, s4, 344
	v_add_u32_e32 v0, s4, v212
	v_lshlrev_b32_e32 v1, 4, v0
	v_add_u32_e32 v2, 0x2b00, v1
	v_lshlrev_b32_e32 v3, 5, v0
	v_add_u32_e32 v4, 0x5600, v3
	s_waitcnt lgkmcnt(0)
	s_add_u32 s6, s14, 0x9890000
	s_addc_u32 s7, s15, 0
	s_add_u32 s8, s14, 0x168d0000
	s_addc_u32 s9, s15, 0
	s_mov_b32 s22, s16
	s_mov_b32 s23, s17
	global_load_dwordx4 v[8:11], v3, s[22:23]
	global_load_dwordx4 v[12:15], v3, s[22:23] offset:16
	global_load_dwordx4 v[32:35], v4, s[22:23]
	global_load_dwordx4 v[36:39], v4, s[22:23] offset:16
	s_add_u32 s22, s22, 0xac00
	s_addc_u32 s23, s23, 0
	global_load_dwordx4 v[16:19], v3, s[22:23]
	global_load_dwordx4 v[20:23], v3, s[22:23] offset:16
	global_load_dwordx4 v[40:43], v4, s[22:23]
	global_load_dwordx4 v[44:47], v4, s[22:23] offset:16
	s_add_u32 s22, s22, 0xac00
	s_addc_u32 s23, s23, 0
	global_load_dwordx4 v[24:27], v3, s[22:23]
	global_load_dwordx4 v[28:31], v3, s[22:23] offset:16
	global_load_dwordx4 v[48:51], v4, s[22:23]
	global_load_dwordx4 v[52:55], v4, s[22:23] offset:16
	global_load_dwordx4 v[56:59], v3, s[18:19]
	global_load_dwordx4 v[60:63], v3, s[18:19] offset:16
	global_load_dwordx4 v[64:67], v4, s[18:19]
	global_load_dwordx4 v[68:71], v4, s[18:19] offset:16
	s_mul_i32 s5, s33, 0x158000
	s_add_u32 s22, s6, s5
	s_addc_u32 s23, s7, 0
	s_and_b32 s5, s33, 31
	s_cmp_eq_u32 s5, 0
	s_cbranch_scc1 .Lp8_nohist
	s_sub_u32 s28, s22, 0xac00
	s_subb_u32 s29, s23, 0
	global_load_dwordx4 v[72:75], v1, s[28:29]
	global_load_dwordx4 v[88:91], v2, s[28:29]
	s_add_u32 s28, s28, 0x5600
	s_addc_u32 s29, s29, 0
	global_load_dwordx4 v[76:79], v1, s[28:29]
	global_load_dwordx4 v[92:95], v2, s[28:29]
	s_branch .Lp8_hist_done
.Lp8_nohist:
	v_mov_b32_e32 v72, 0
	v_mov_b32_e32 v88, 0
	v_mov_b32_e32 v73, 0
	v_mov_b32_e32 v89, 0
	v_mov_b32_e32 v74, 0
	v_mov_b32_e32 v90, 0
	v_mov_b32_e32 v75, 0
	v_mov_b32_e32 v91, 0
	v_mov_b32_e32 v76, 0
	v_mov_b32_e32 v92, 0
	v_mov_b32_e32 v77, 0
	v_mov_b32_e32 v93, 0
	v_mov_b32_e32 v78, 0
	v_mov_b32_e32 v94, 0
	v_mov_b32_e32 v79, 0
	v_mov_b32_e32 v95, 0
.Lp8_hist_done:
	global_load_dwordx4 v[80:83], v1, s[22:23]
	global_load_dwordx4 v[96:99], v2, s[22:23]
	s_add_u32 s22, s22, 0x5600
	s_addc_u32 s23, s23, 0
	global_load_dwordx4 v[84:87], v1, s[22:23]
	global_load_dwordx4 v[100:103], v2, s[22:23]
	s_mul_i32 s5, s33, 0x15800
	s_add_u32 s22, s6, s5
	s_addc_u32 s23, s7, 0
	s_add_u32 s22, s22, 0xac00000
	s_addc_u32 s23, s23, 0
	global_load_dwordx4 v[104:107], v1, s[22:23]
	global_load_dwordx4 v[120:123], v2, s[22:23]
	s_add_u32 s22, s22, 0x5600
	s_addc_u32 s23, s23, 0
	global_load_dwordx4 v[108:111], v1, s[22:23]
	global_load_dwordx4 v[124:127], v2, s[22:23]
	s_add_u32 s22, s22, 0x5600
	s_addc_u32 s23, s23, 0
	global_load_dwordx4 v[112:115], v1, s[22:23]
	global_load_dwordx4 v[128:131], v2, s[22:23]
	s_add_u32 s22, s22, 0x5600
	s_addc_u32 s23, s23, 0
	global_load_dwordx4 v[116:119], v1, s[22:23]
	global_load_dwordx4 v[132:135], v2, s[22:23]
	s_add_u32 s26, s20, s5
	s_addc_u32 s27, s21, 0
	global_load_dwordx4 v[136:139], v3, s[26:27]
	global_load_dwordx4 v[140:143], v3, s[26:27] offset:16
	global_load_dwordx4 v[152:155], v4, s[26:27]
	global_load_dwordx4 v[156:159], v4, s[26:27] offset:16
	s_add_u32 s26, s26, 0xac00
	s_addc_u32 s27, s27, 0
	global_load_dwordx4 v[144:147], v3, s[26:27]
	global_load_dwordx4 v[148:151], v3, s[26:27] offset:16
	global_load_dwordx4 v[160:163], v4, s[26:27]
	global_load_dwordx4 v[164:167], v4, s[26:27] offset:16
	s_mul_i32 s5, s33, 0xac000
	s_add_u32 s24, s8, s5
	s_addc_u32 s25, s9, 0
	s_waitcnt vmcnt(16)
	v_lshlrev_b32_e32 v168, 16, v72
	v_and_b32_e32 v169, 0xffff0000, v72
	v_lshlrev_b32_e32 v170, 16, v73
	v_and_b32_e32 v171, 0xffff0000, v73
	v_lshlrev_b32_e32 v172, 16, v74
	v_and_b32_e32 v173, 0xffff0000, v74
	v_lshlrev_b32_e32 v174, 16, v75
	v_and_b32_e32 v175, 0xffff0000, v75
	v_lshlrev_b32_e32 v192, 16, v88
	v_and_b32_e32 v193, 0xffff0000, v88
	v_lshlrev_b32_e32 v194, 16, v89
	v_and_b32_e32 v195, 0xffff0000, v89
	v_lshlrev_b32_e32 v196, 16, v90
	v_and_b32_e32 v197, 0xffff0000, v90
	v_lshlrev_b32_e32 v198, 16, v91
	v_and_b32_e32 v199, 0xffff0000, v91
	v_lshlrev_b32_e32 v176, 16, v76
	v_and_b32_e32 v177, 0xffff0000, v76
	v_lshlrev_b32_e32 v178, 16, v77
	v_and_b32_e32 v179, 0xffff0000, v77
	v_lshlrev_b32_e32 v180, 16, v78
	v_and_b32_e32 v181, 0xffff0000, v78
	v_lshlrev_b32_e32 v182, 16, v79
	v_and_b32_e32 v183, 0xffff0000, v79
	v_lshlrev_b32_e32 v200, 16, v92
	v_and_b32_e32 v201, 0xffff0000, v92
	v_lshlrev_b32_e32 v202, 16, v93
	v_and_b32_e32 v203, 0xffff0000, v93
	v_lshlrev_b32_e32 v204, 16, v94
	v_and_b32_e32 v205, 0xffff0000, v94
	v_lshlrev_b32_e32 v206, 16, v95
	v_and_b32_e32 v207, 0xffff0000, v95
	v_lshlrev_b32_e32 v184, 16, v80
	v_and_b32_e32 v185, 0xffff0000, v80
	v_lshlrev_b32_e32 v186, 16, v81
	v_and_b32_e32 v187, 0xffff0000, v81
	v_lshlrev_b32_e32 v188, 16, v82
	v_and_b32_e32 v189, 0xffff0000, v82
	v_lshlrev_b32_e32 v190, 16, v83
	v_and_b32_e32 v191, 0xffff0000, v83
	v_lshlrev_b32_e32 v214, 16, v96
	v_and_b32_e32 v215, 0xffff0000, v96
	v_lshlrev_b32_e32 v216, 16, v97
	v_and_b32_e32 v217, 0xffff0000, v97
	v_lshlrev_b32_e32 v218, 16, v98
	v_and_b32_e32 v219, 0xffff0000, v98
	v_lshlrev_b32_e32 v220, 16, v99
; __device__ __forceinline__ float siluf_(float x) { return x * __builtin_amdgcn_rcpf(1.f + __expf(-x)); }
; template <int NT, bool SAMPLE>
; __device__ __forceinline__ void ffn_item(const bf16_t* U, int row0, bool has_hist, const float* st, int cgi, const float* w, const float* bias, bf16_t* ACT, float* state_out) {
;     ...
;     for (int t = 0; t < NT; ++t) {
;         float cg_[8], cv_[8], o[8];
;         unpack8(rg[t], cg_); unpack8(rv[t], cv_);
; #pragma unroll
;         for (int e = 0; e < 8; ++e) {
;             const float gg = g0[e] * wg[0][e] + g1[e] * wg[1][e] + cg_[e] * wg[2][e] + bg[e];
;             const float vv = v0[e] * wv[0][e] + v1[e] * wv[1][e] + cv_[e] * wv[2][e] + bvv[e];
;             o[e] = siluf_(gg) * vv; g0[e] = g1[e]; g1[e] = cg_[e]; v0[e] = v1[e]; v1[e] = cv_[e]; }
;         *(u32x4*)(ACT + (size_t)(row0 + t) * FF + c0) = pack8(o);
	v_and_b32_e32 v221, 0xffff0000, v99
	v_pk_mul_f32 v[222:223], v[168:169], v[8:9]
	v_pk_fma_f32 v[222:223], v[176:177], v[16:17], v[222:223]
	v_pk_fma_f32 v[222:223], v[184:185], v[24:25], v[222:223]
	v_pk_add_f32 v[222:223], v[222:223], v[56:57]
	v_pk_mul_f32 v[224:225], v[170:171], v[10:11]
	v_pk_fma_f32 v[224:225], v[178:179], v[18:19], v[224:225]
	v_pk_fma_f32 v[224:225], v[186:187], v[26:27], v[224:225]
	v_pk_add_f32 v[224:225], v[224:225], v[58:59]
	v_pk_mul_f32 v[226:227], v[172:173], v[12:13]
	v_pk_fma_f32 v[226:227], v[180:181], v[20:21], v[226:227]
	v_pk_fma_f32 v[226:227], v[188:189], v[28:29], v[226:227]
	v_pk_add_f32 v[226:227], v[226:227], v[60:61]
	v_pk_mul_f32 v[228:229], v[174:175], v[14:15]
	v_pk_fma_f32 v[228:229], v[182:183], v[22:23], v[228:229]
	v_pk_fma_f32 v[228:229], v[190:191], v[30:31], v[228:229]
	v_pk_add_f32 v[228:229], v[228:229], v[62:63]
	v_pk_mul_f32 v[230:231], v[192:193], v[32:33]
	v_pk_fma_f32 v[230:231], v[200:201], v[40:41], v[230:231]
	v_pk_fma_f32 v[230:231], v[214:215], v[48:49], v[230:231]
	v_pk_add_f32 v[230:231], v[230:231], v[64:65]
	v_pk_mul_f32 v[232:233], v[194:195], v[34:35]
	v_pk_fma_f32 v[232:233], v[202:203], v[42:43], v[232:233]
	v_pk_fma_f32 v[232:233], v[216:217], v[50:51], v[232:233]
	v_pk_add_f32 v[232:233], v[232:233], v[66:67]
	v_pk_mul_f32 v[234:235], v[196:197], v[36:37]
	v_pk_fma_f32 v[234:235], v[204:205], v[44:45], v[234:235]
	v_pk_fma_f32 v[234:235], v[218:219], v[52:53], v[234:235]
	v_pk_add_f32 v[234:235], v[234:235], v[68:69]
	v_pk_mul_f32 v[236:237], v[198:199], v[38:39]
	v_pk_fma_f32 v[236:237], v[206:207], v[46:47], v[236:237]
	v_pk_fma_f32 v[236:237], v[220:221], v[54:55], v[236:237]
	v_pk_add_f32 v[236:237], v[236:237], v[70:71]
	v_mul_f32_e32 v238, 0xbfb8aa3b, v222
	v_mul_f32_e32 v239, 0xbfb8aa3b, v223
	v_mul_f32_e32 v240, 0xbfb8aa3b, v224
	v_mul_f32_e32 v241, 0xbfb8aa3b, v225
	v_mul_f32_e32 v242, 0xbfb8aa3b, v226
	v_mul_f32_e32 v243, 0xbfb8aa3b, v227
	v_mul_f32_e32 v244, 0xbfb8aa3b, v228
	v_mul_f32_e32 v245, 0xbfb8aa3b, v229
	v_exp_f32_e32 v238, v238
	v_exp_f32_e32 v239, v239
	v_exp_f32_e32 v240, v240
	v_exp_f32_e32 v241, v241
	v_exp_f32_e32 v242, v242
	v_exp_f32_e32 v243, v243
	v_exp_f32_e32 v244, v244
	v_exp_f32_e32 v245, v245
	v_add_f32_e32 v238, 1.0, v238
	v_add_f32_e32 v239, 1.0, v239
	v_add_f32_e32 v240, 1.0, v240
	v_add_f32_e32 v241, 1.0, v241
	v_add_f32_e32 v242, 1.0, v242
	v_add_f32_e32 v243, 1.0, v243
	v_add_f32_e32 v244, 1.0, v244
	v_add_f32_e32 v245, 1.0, v245
	v_rcp_f32_e32 v238, v238
	v_rcp_f32_e32 v239, v239
	v_rcp_f32_e32 v240, v240
	v_rcp_f32_e32 v241, v241
	v_rcp_f32_e32 v242, v242
	v_rcp_f32_e32 v243, v243
	v_rcp_f32_e32 v244, v244
	v_rcp_f32_e32 v245, v245
	v_mul_f32_e32 v238, v222, v238
	v_mul_f32_e32 v239, v223, v239
	v_mul_f32_e32 v240, v224, v240
	v_mul_f32_e32 v241, v225, v241
	v_mul_f32_e32 v242, v226, v242
	v_mul_f32_e32 v243, v227, v243
	v_mul_f32_e32 v244, v228, v244
	v_mul_f32_e32 v245, v229, v245
	v_mul_f32_e32 v238, v238, v230
	v_mul_f32_e32 v239, v239, v231
	v_mul_f32_e32 v240, v240, v232
	v_mul_f32_e32 v241, v241, v233
	v_mul_f32_e32 v242, v242, v234
	v_mul_f32_e32 v243, v243, v235
	v_mul_f32_e32 v244, v244, v236
	v_mul_f32_e32 v245, v245, v237
	v_cvt_pk_bf16_f32 v246, v238, v239
	v_cvt_pk_bf16_f32 v247, v240, v241
	v_cvt_pk_bf16_f32 v248, v242, v243
	v_cvt_pk_bf16_f32 v249, v244, v245
	global_store_dwordx4 v1, v[246:249], s[24:25]
	s_add_u32 s24, s24, 0x2b00
	s_addc_u32 s25, s25, 0
	v_lshlrev_b32_e32 v168, 16, v84
	v_and_b32_e32 v169, 0xffff0000, v84
	v_lshlrev_b32_e32 v170, 16, v85
	v_and_b32_e32 v171, 0xffff0000, v85
	v_lshlrev_b32_e32 v172, 16, v86
	v_and_b32_e32 v173, 0xffff0000, v86
	v_lshlrev_b32_e32 v174, 16, v87
	v_and_b32_e32 v175, 0xffff0000, v87
	v_lshlrev_b32_e32 v192, 16, v100
	v_and_b32_e32 v193, 0xffff0000, v100
	v_lshlrev_b32_e32 v194, 16, v101
	v_and_b32_e32 v195, 0xffff0000, v101
	v_lshlrev_b32_e32 v196, 16, v102
	v_and_b32_e32 v197, 0xffff0000, v102
	v_lshlrev_b32_e32 v198, 16, v103
	v_and_b32_e32 v199, 0xffff0000, v103
	v_pk_mul_f32 v[222:223], v[176:177], v[8:9]
	v_pk_fma_f32 v[222:223], v[184:185], v[16:17], v[222:223]
	v_pk_fma_f32 v[222:223], v[168:169], v[24:25], v[222:223]
	v_pk_add_f32 v[222:223], v[222:223], v[56:57]
	v_pk_mul_f32 v[224:225], v[178:179], v[10:11]
	v_pk_fma_f32 v[224:225], v[186:187], v[18:19], v[224:225]
	v_pk_fma_f32 v[224:225], v[170:171], v[26:27], v[224:225]
	v_pk_add_f32 v[224:225], v[224:225], v[58:59]
	v_pk_mul_f32 v[226:227], v[180:181], v[12:13]
	v_pk_fma_f32 v[226:227], v[188:189], v[20:21], v[226:227]
	v_pk_fma_f32 v[226:227], v[172:173], v[28:29], v[226:227]
	v_pk_add_f32 v[226:227], v[226:227], v[60:61]
	v_pk_mul_f32 v[228:229], v[182:183], v[14:15]
	v_pk_fma_f32 v[228:229], v[190:191], v[22:23], v[228:229]
	v_pk_fma_f32 v[228:229], v[174:175], v[30:31], v[228:229]
	v_pk_add_f32 v[228:229], v[228:229], v[62:63]
	v_pk_mul_f32 v[230:231], v[200:201], v[32:33]
	v_pk_fma_f32 v[230:231], v[214:215], v[40:41], v[230:231]
	v_pk_fma_f32 v[230:231], v[192:193], v[48:49], v[230:231]
	v_pk_add_f32 v[230:231], v[230:231], v[64:65]
	v_pk_mul_f32 v[232:233], v[202:203], v[34:35]
	v_pk_fma_f32 v[232:233], v[216:217], v[42:43], v[232:233]
	v_pk_fma_f32 v[232:233], v[194:195], v[50:51], v[232:233]
	v_pk_add_f32 v[232:233], v[232:233], v[66:67]
	v_pk_mul_f32 v[234:235], v[204:205], v[36:37]
	v_pk_fma_f32 v[234:235], v[218:219], v[44:45], v[234:235]
	v_pk_fma_f32 v[234:235], v[196:197], v[52:53], v[234:235]
	v_pk_add_f32 v[234:235], v[234:235], v[68:69]
	v_pk_mul_f32 v[236:237], v[206:207], v[38:39]
	v_pk_fma_f32 v[236:237], v[220:221], v[46:47], v[236:237]
	v_pk_fma_f32 v[236:237], v[198:199], v[54:55], v[236:237]
; __device__ __forceinline__ float siluf_(float x) { return x * __builtin_amdgcn_rcpf(1.f + __expf(-x)); }
; template <int NT, bool SAMPLE>
; __device__ __forceinline__ void ffn_item(const bf16_t* U, int row0, bool has_hist, const float* st, int cgi, const float* w, const float* bias, bf16_t* ACT, float* state_out) {
;     ...
;     for (int t = 0; t < NT; ++t) {
;         float cg_[8], cv_[8], o[8];
;         unpack8(rg[t], cg_); unpack8(rv[t], cv_);
; #pragma unroll
;         for (int e = 0; e < 8; ++e) {
;             const float gg = g0[e] * wg[0][e] + g1[e] * wg[1][e] + cg_[e] * wg[2][e] + bg[e];
;             const float vv = v0[e] * wv[0][e] + v1[e] * wv[1][e] + cv_[e] * wv[2][e] + bvv[e];
;             o[e] = siluf_(gg) * vv; g0[e] = g1[e]; g1[e] = cg_[e]; v0[e] = v1[e]; v1[e] = cv_[e]; }
;         *(u32x4*)(ACT + (size_t)(row0 + t) * FF + c0) = pack8(o);
	v_pk_add_f32 v[236:237], v[236:237], v[70:71]
	v_mul_f32_e32 v238, 0xbfb8aa3b, v222
	v_mul_f32_e32 v239, 0xbfb8aa3b, v223
	v_mul_f32_e32 v240, 0xbfb8aa3b, v224
	v_mul_f32_e32 v241, 0xbfb8aa3b, v225
	v_mul_f32_e32 v242, 0xbfb8aa3b, v226
	v_mul_f32_e32 v243, 0xbfb8aa3b, v227
	v_mul_f32_e32 v244, 0xbfb8aa3b, v228
	v_mul_f32_e32 v245, 0xbfb8aa3b, v229
	v_exp_f32_e32 v238, v238
	v_exp_f32_e32 v239, v239
	v_exp_f32_e32 v240, v240
	v_exp_f32_e32 v241, v241
	v_exp_f32_e32 v242, v242
	v_exp_f32_e32 v243, v243
	v_exp_f32_e32 v244, v244
	v_exp_f32_e32 v245, v245
	v_add_f32_e32 v238, 1.0, v238
	v_add_f32_e32 v239, 1.0, v239
	v_add_f32_e32 v240, 1.0, v240
	v_add_f32_e32 v241, 1.0, v241
	v_add_f32_e32 v242, 1.0, v242
	v_add_f32_e32 v243, 1.0, v243
	v_add_f32_e32 v244, 1.0, v244
	v_add_f32_e32 v245, 1.0, v245
	v_rcp_f32_e32 v238, v238
	v_rcp_f32_e32 v239, v239
	v_rcp_f32_e32 v240, v240
	v_rcp_f32_e32 v241, v241
	v_rcp_f32_e32 v242, v242
	v_rcp_f32_e32 v243, v243
	v_rcp_f32_e32 v244, v244
	v_rcp_f32_e32 v245, v245
	v_mul_f32_e32 v238, v222, v238
	v_mul_f32_e32 v239, v223, v239
	v_mul_f32_e32 v240, v224, v240
	v_mul_f32_e32 v241, v225, v241
	v_mul_f32_e32 v242, v226, v242
	v_mul_f32_e32 v243, v227, v243
	v_mul_f32_e32 v244, v228, v244
	v_mul_f32_e32 v245, v229, v245
	v_mul_f32_e32 v238, v238, v230
	v_mul_f32_e32 v239, v239, v231
	v_mul_f32_e32 v240, v240, v232
	v_mul_f32_e32 v241, v241, v233
	v_mul_f32_e32 v242, v242, v234
	v_mul_f32_e32 v243, v243, v235
	v_mul_f32_e32 v244, v244, v236
	v_mul_f32_e32 v245, v245, v237
	v_cvt_pk_bf16_f32 v246, v238, v239
	v_cvt_pk_bf16_f32 v247, v240, v241
	v_cvt_pk_bf16_f32 v248, v242, v243
	v_cvt_pk_bf16_f32 v249, v244, v245
	global_store_dwordx4 v1, v[246:249], s[24:25]
	s_mul_i32 s5, s33, 0xac00
	s_add_u32 s24, s8, s5
	s_addc_u32 s25, s9, 0
	s_add_u32 s24, s24, 0x5600000
	s_addc_u32 s25, s25, 0
	s_waitcnt vmcnt(2)
	v_lshlrev_b32_e32 v168, 16, v104
	v_and_b32_e32 v169, 0xffff0000, v104
	v_lshlrev_b32_e32 v170, 16, v105
	v_and_b32_e32 v171, 0xffff0000, v105
	v_lshlrev_b32_e32 v172, 16, v106
	v_and_b32_e32 v173, 0xffff0000, v106
	v_lshlrev_b32_e32 v174, 16, v107
	v_and_b32_e32 v175, 0xffff0000, v107
	v_lshlrev_b32_e32 v192, 16, v120
	v_and_b32_e32 v193, 0xffff0000, v120
	v_lshlrev_b32_e32 v194, 16, v121
	v_and_b32_e32 v195, 0xffff0000, v121
	v_lshlrev_b32_e32 v196, 16, v122
	v_and_b32_e32 v197, 0xffff0000, v122
	v_lshlrev_b32_e32 v198, 16, v123
	v_and_b32_e32 v199, 0xffff0000, v123
	v_pk_mul_f32 v[222:223], v[136:137], v[8:9]
	v_pk_fma_f32 v[222:223], v[144:145], v[16:17], v[222:223]
	v_pk_fma_f32 v[222:223], v[168:169], v[24:25], v[222:223]
	v_pk_add_f32 v[222:223], v[222:223], v[56:57]
	v_pk_mul_f32 v[224:225], v[138:139], v[10:11]
	v_pk_fma_f32 v[224:225], v[146:147], v[18:19], v[224:225]
	v_pk_fma_f32 v[224:225], v[170:171], v[26:27], v[224:225]
	v_pk_add_f32 v[224:225], v[224:225], v[58:59]
	v_pk_mul_f32 v[226:227], v[140:141], v[12:13]
	v_pk_fma_f32 v[226:227], v[148:149], v[20:21], v[226:227]
	v_pk_fma_f32 v[226:227], v[172:173], v[28:29], v[226:227]
	v_pk_add_f32 v[226:227], v[226:227], v[60:61]
	v_pk_mul_f32 v[228:229], v[142:143], v[14:15]
	v_pk_fma_f32 v[228:229], v[150:151], v[22:23], v[228:229]
	v_pk_fma_f32 v[228:229], v[174:175], v[30:31], v[228:229]
	v_pk_add_f32 v[228:229], v[228:229], v[62:63]
	v_pk_mul_f32 v[230:231], v[152:153], v[32:33]
	v_pk_fma_f32 v[230:231], v[160:161], v[40:41], v[230:231]
	v_pk_fma_f32 v[230:231], v[192:193], v[48:49], v[230:231]
	v_pk_add_f32 v[230:231], v[230:231], v[64:65]
	v_pk_mul_f32 v[232:233], v[154:155], v[34:35]
	v_pk_fma_f32 v[232:233], v[162:163], v[42:43], v[232:233]
	v_pk_fma_f32 v[232:233], v[194:195], v[50:51], v[232:233]
	v_pk_add_f32 v[232:233], v[232:233], v[66:67]
	v_pk_mul_f32 v[234:235], v[156:157], v[36:37]
	v_pk_fma_f32 v[234:235], v[164:165], v[44:45], v[234:235]
	v_pk_fma_f32 v[234:235], v[196:197], v[52:53], v[234:235]
	v_pk_add_f32 v[234:235], v[234:235], v[68:69]
	v_pk_mul_f32 v[236:237], v[158:159], v[38:39]
	v_pk_fma_f32 v[236:237], v[166:167], v[46:47], v[236:237]
	v_pk_fma_f32 v[236:237], v[198:199], v[54:55], v[236:237]
	v_pk_add_f32 v[236:237], v[236:237], v[70:71]
	v_mul_f32_e32 v238, 0xbfb8aa3b, v222
	v_mul_f32_e32 v239, 0xbfb8aa3b, v223
	v_mul_f32_e32 v240, 0xbfb8aa3b, v224
	v_mul_f32_e32 v241, 0xbfb8aa3b, v225
	v_mul_f32_e32 v242, 0xbfb8aa3b, v226
	v_mul_f32_e32 v243, 0xbfb8aa3b, v227
	v_mul_f32_e32 v244, 0xbfb8aa3b, v228
	v_mul_f32_e32 v245, 0xbfb8aa3b, v229
	v_exp_f32_e32 v238, v238
	v_exp_f32_e32 v239, v239
	v_exp_f32_e32 v240, v240
	v_exp_f32_e32 v241, v241
	v_exp_f32_e32 v242, v242
	v_exp_f32_e32 v243, v243
	v_exp_f32_e32 v244, v244
	v_exp_f32_e32 v245, v245
	v_add_f32_e32 v238, 1.0, v238
	v_add_f32_e32 v239, 1.0, v239
	v_add_f32_e32 v240, 1.0, v240
	v_add_f32_e32 v241, 1.0, v241
	v_add_f32_e32 v242, 1.0, v242
	v_add_f32_e32 v243, 1.0, v243
	v_add_f32_e32 v244, 1.0, v244
	v_add_f32_e32 v245, 1.0, v245
	v_rcp_f32_e32 v238, v238
	v_rcp_f32_e32 v239, v239
	v_rcp_f32_e32 v240, v240
	v_rcp_f32_e32 v241, v241
	v_rcp_f32_e32 v242, v242
	v_rcp_f32_e32 v243, v243
	v_rcp_f32_e32 v244, v244
	v_rcp_f32_e32 v245, v245
	v_mul_f32_e32 v238, v222, v238
	v_mul_f32_e32 v239, v223, v239
	v_mul_f32_e32 v240, v224, v240
	v_mul_f32_e32 v241, v225, v241
	v_mul_f32_e32 v242, v226, v242
	v_mul_f32_e32 v243, v227, v243
	v_mul_f32_e32 v244, v228, v244
	v_mul_f32_e32 v245, v229, v245
	v_mul_f32_e32 v238, v238, v230
	v_mul_f32_e32 v239, v239, v231
	v_mul_f32_e32 v240, v240, v232
	v_mul_f32_e32 v241, v241, v233
	v_mul_f32_e32 v242, v242, v234
	v_mul_f32_e32 v243, v243, v235
	v_mul_f32_e32 v244, v244, v236
	v_mul_f32_e32 v245, v245, v237
	v_cvt_pk_bf16_f32 v246, v238, v239
; __device__ __forceinline__ float siluf_(float x) { return x * __builtin_amdgcn_rcpf(1.f + __expf(-x)); }
; template <int NT, bool SAMPLE>
; __device__ __forceinline__ void ffn_item(const bf16_t* U, int row0, bool has_hist, const float* st, int cgi, const float* w, const float* bias, bf16_t* ACT, float* state_out) {
;     ...
;     for (int t = 0; t < NT; ++t) {
;         float cg_[8], cv_[8], o[8];
;         unpack8(rg[t], cg_); unpack8(rv[t], cv_);
; #pragma unroll
;         for (int e = 0; e < 8; ++e) {
;             const float gg = g0[e] * wg[0][e] + g1[e] * wg[1][e] + cg_[e] * wg[2][e] + bg[e];
;             const float vv = v0[e] * wv[0][e] + v1[e] * wv[1][e] + cv_[e] * wv[2][e] + bvv[e];
;             o[e] = siluf_(gg) * vv; g0[e] = g1[e]; g1[e] = cg_[e]; v0[e] = v1[e]; v1[e] = cv_[e]; }
;         *(u32x4*)(ACT + (size_t)(row0 + t) * FF + c0) = pack8(o);
	v_cvt_pk_bf16_f32 v247, v240, v241
	v_cvt_pk_bf16_f32 v248, v242, v243
	v_cvt_pk_bf16_f32 v249, v244, v245
	global_store_dwordx4 v1, v[246:249], s[24:25]
	s_add_u32 s24, s24, 0x2b00
	s_addc_u32 s25, s25, 0
	v_lshlrev_b32_e32 v176, 16, v108
	v_and_b32_e32 v177, 0xffff0000, v108
	v_lshlrev_b32_e32 v178, 16, v109
	v_and_b32_e32 v179, 0xffff0000, v109
	v_lshlrev_b32_e32 v180, 16, v110
	v_and_b32_e32 v181, 0xffff0000, v110
	v_lshlrev_b32_e32 v182, 16, v111
	v_and_b32_e32 v183, 0xffff0000, v111
	v_lshlrev_b32_e32 v200, 16, v124
	v_and_b32_e32 v201, 0xffff0000, v124
	v_lshlrev_b32_e32 v202, 16, v125
	v_and_b32_e32 v203, 0xffff0000, v125
	v_lshlrev_b32_e32 v204, 16, v126
	v_and_b32_e32 v205, 0xffff0000, v126
	v_lshlrev_b32_e32 v206, 16, v127
	v_and_b32_e32 v207, 0xffff0000, v127
	v_pk_mul_f32 v[222:223], v[144:145], v[8:9]
	v_pk_fma_f32 v[222:223], v[168:169], v[16:17], v[222:223]
	v_pk_fma_f32 v[222:223], v[176:177], v[24:25], v[222:223]
	v_pk_add_f32 v[222:223], v[222:223], v[56:57]
	v_pk_mul_f32 v[224:225], v[146:147], v[10:11]
	v_pk_fma_f32 v[224:225], v[170:171], v[18:19], v[224:225]
	v_pk_fma_f32 v[224:225], v[178:179], v[26:27], v[224:225]
	v_pk_add_f32 v[224:225], v[224:225], v[58:59]
	v_pk_mul_f32 v[226:227], v[148:149], v[12:13]
	v_pk_fma_f32 v[226:227], v[172:173], v[20:21], v[226:227]
	v_pk_fma_f32 v[226:227], v[180:181], v[28:29], v[226:227]
	v_pk_add_f32 v[226:227], v[226:227], v[60:61]
	v_pk_mul_f32 v[228:229], v[150:151], v[14:15]
	v_pk_fma_f32 v[228:229], v[174:175], v[22:23], v[228:229]
	v_pk_fma_f32 v[228:229], v[182:183], v[30:31], v[228:229]
	v_pk_add_f32 v[228:229], v[228:229], v[62:63]
	v_pk_mul_f32 v[230:231], v[160:161], v[32:33]
	v_pk_fma_f32 v[230:231], v[192:193], v[40:41], v[230:231]
	v_pk_fma_f32 v[230:231], v[200:201], v[48:49], v[230:231]
	v_pk_add_f32 v[230:231], v[230:231], v[64:65]
	v_pk_mul_f32 v[232:233], v[162:163], v[34:35]
	v_pk_fma_f32 v[232:233], v[194:195], v[42:43], v[232:233]
	v_pk_fma_f32 v[232:233], v[202:203], v[50:51], v[232:233]
	v_pk_add_f32 v[232:233], v[232:233], v[66:67]
	v_pk_mul_f32 v[234:235], v[164:165], v[36:37]
	v_pk_fma_f32 v[234:235], v[196:197], v[44:45], v[234:235]
	v_pk_fma_f32 v[234:235], v[204:205], v[52:53], v[234:235]
	v_pk_add_f32 v[234:235], v[234:235], v[68:69]
	v_pk_mul_f32 v[236:237], v[166:167], v[38:39]
	v_pk_fma_f32 v[236:237], v[198:199], v[46:47], v[236:237]
	v_pk_fma_f32 v[236:237], v[206:207], v[54:55], v[236:237]
	v_pk_add_f32 v[236:237], v[236:237], v[70:71]
	v_mul_f32_e32 v238, 0xbfb8aa3b, v222
	v_mul_f32_e32 v239, 0xbfb8aa3b, v223
	v_mul_f32_e32 v240, 0xbfb8aa3b, v224
	v_mul_f32_e32 v241, 0xbfb8aa3b, v225
	v_mul_f32_e32 v242, 0xbfb8aa3b, v226
	v_mul_f32_e32 v243, 0xbfb8aa3b, v227
	v_mul_f32_e32 v244, 0xbfb8aa3b, v228
	v_mul_f32_e32 v245, 0xbfb8aa3b, v229
	v_exp_f32_e32 v238, v238
	v_exp_f32_e32 v239, v239
	v_exp_f32_e32 v240, v240
	v_exp_f32_e32 v241, v241
	v_exp_f32_e32 v242, v242
	v_exp_f32_e32 v243, v243
	v_exp_f32_e32 v244, v244
	v_exp_f32_e32 v245, v245
	v_add_f32_e32 v238, 1.0, v238
	v_add_f32_e32 v239, 1.0, v239
	v_add_f32_e32 v240, 1.0, v240
	v_add_f32_e32 v241, 1.0, v241
	v_add_f32_e32 v242, 1.0, v242
	v_add_f32_e32 v243, 1.0, v243
	v_add_f32_e32 v244, 1.0, v244
	v_add_f32_e32 v245, 1.0, v245
	v_rcp_f32_e32 v238, v238
	v_rcp_f32_e32 v239, v239
	v_rcp_f32_e32 v240, v240
	v_rcp_f32_e32 v241, v241
	v_rcp_f32_e32 v242, v242
	v_rcp_f32_e32 v243, v243
	v_rcp_f32_e32 v244, v244
	v_rcp_f32_e32 v245, v245
	v_mul_f32_e32 v238, v222, v238
	v_mul_f32_e32 v239, v223, v239
	v_mul_f32_e32 v240, v224, v240
	v_mul_f32_e32 v241, v225, v241
	v_mul_f32_e32 v242, v226, v242
	v_mul_f32_e32 v243, v227, v243
	v_mul_f32_e32 v244, v228, v244
	v_mul_f32_e32 v245, v229, v245
	v_mul_f32_e32 v238, v238, v230
	v_mul_f32_e32 v239, v239, v231
	v_mul_f32_e32 v240, v240, v232
	v_mul_f32_e32 v241, v241, v233
	v_mul_f32_e32 v242, v242, v234
	v_mul_f32_e32 v243, v243, v235
	v_mul_f32_e32 v244, v244, v236
	v_mul_f32_e32 v245, v245, v237
	v_cvt_pk_bf16_f32 v246, v238, v239
	v_cvt_pk_bf16_f32 v247, v240, v241
	v_cvt_pk_bf16_f32 v248, v242, v243
	v_cvt_pk_bf16_f32 v249, v244, v245
	global_store_dwordx4 v1, v[246:249], s[24:25]
	s_add_u32 s24, s24, 0x2b00
	s_addc_u32 s25, s25, 0
	v_lshlrev_b32_e32 v184, 16, v112
	v_and_b32_e32 v185, 0xffff0000, v112
	v_lshlrev_b32_e32 v186, 16, v113
	v_and_b32_e32 v187, 0xffff0000, v113
	v_lshlrev_b32_e32 v188, 16, v114
	v_and_b32_e32 v189, 0xffff0000, v114
	v_lshlrev_b32_e32 v190, 16, v115
	v_and_b32_e32 v191, 0xffff0000, v115
	v_lshlrev_b32_e32 v214, 16, v128
	v_and_b32_e32 v215, 0xffff0000, v128
	v_lshlrev_b32_e32 v216, 16, v129
	v_and_b32_e32 v217, 0xffff0000, v129
	v_lshlrev_b32_e32 v218, 16, v130
	v_and_b32_e32 v219, 0xffff0000, v130
	v_lshlrev_b32_e32 v220, 16, v131
	v_and_b32_e32 v221, 0xffff0000, v131
	v_pk_mul_f32 v[222:223], v[168:169], v[8:9]
	v_pk_fma_f32 v[222:223], v[176:177], v[16:17], v[222:223]
	v_pk_fma_f32 v[222:223], v[184:185], v[24:25], v[222:223]
	v_pk_add_f32 v[222:223], v[222:223], v[56:57]
	v_pk_mul_f32 v[224:225], v[170:171], v[10:11]
	v_pk_fma_f32 v[224:225], v[178:179], v[18:19], v[224:225]
	v_pk_fma_f32 v[224:225], v[186:187], v[26:27], v[224:225]
	v_pk_add_f32 v[224:225], v[224:225], v[58:59]
	v_pk_mul_f32 v[226:227], v[172:173], v[12:13]
	v_pk_fma_f32 v[226:227], v[180:181], v[20:21], v[226:227]
	v_pk_fma_f32 v[226:227], v[188:189], v[28:29], v[226:227]
	v_pk_add_f32 v[226:227], v[226:227], v[60:61]
	v_pk_mul_f32 v[228:229], v[174:175], v[14:15]
	v_pk_fma_f32 v[228:229], v[182:183], v[22:23], v[228:229]
	v_pk_fma_f32 v[228:229], v[190:191], v[30:31], v[228:229]
	v_pk_add_f32 v[228:229], v[228:229], v[62:63]
; __device__ __forceinline__ float siluf_(float x) { return x * __builtin_amdgcn_rcpf(1.f + __expf(-x)); }
; template <int NT, bool SAMPLE>
; __device__ __forceinline__ void ffn_item(const bf16_t* U, int row0, bool has_hist, const float* st, int cgi, const float* w, const float* bias, bf16_t* ACT, float* state_out) {
;     ...
;     for (int t = 0; t < NT; ++t) {
;         float cg_[8], cv_[8], o[8];
;         unpack8(rg[t], cg_); unpack8(rv[t], cv_);
; #pragma unroll
;         for (int e = 0; e < 8; ++e) {
;             const float gg = g0[e] * wg[0][e] + g1[e] * wg[1][e] + cg_[e] * wg[2][e] + bg[e];
;             const float vv = v0[e] * wv[0][e] + v1[e] * wv[1][e] + cv_[e] * wv[2][e] + bvv[e];
;             o[e] = siluf_(gg) * vv; g0[e] = g1[e]; g1[e] = cg_[e]; v0[e] = v1[e]; v1[e] = cv_[e]; }
;         *(u32x4*)(ACT + (size_t)(row0 + t) * FF + c0) = pack8(o);
	v_pk_mul_f32 v[230:231], v[192:193], v[32:33]
	v_pk_fma_f32 v[230:231], v[200:201], v[40:41], v[230:231]
	v_pk_fma_f32 v[230:231], v[214:215], v[48:49], v[230:231]
	v_pk_add_f32 v[230:231], v[230:231], v[64:65]
	v_pk_mul_f32 v[232:233], v[194:195], v[34:35]
	v_pk_fma_f32 v[232:233], v[202:203], v[42:43], v[232:233]
	v_pk_fma_f32 v[232:233], v[216:217], v[50:51], v[232:233]
	v_pk_add_f32 v[232:233], v[232:233], v[66:67]
	v_pk_mul_f32 v[234:235], v[196:197], v[36:37]
	v_pk_fma_f32 v[234:235], v[204:205], v[44:45], v[234:235]
	v_pk_fma_f32 v[234:235], v[218:219], v[52:53], v[234:235]
	v_pk_add_f32 v[234:235], v[234:235], v[68:69]
	v_pk_mul_f32 v[236:237], v[198:199], v[38:39]
	v_pk_fma_f32 v[236:237], v[206:207], v[46:47], v[236:237]
	v_pk_fma_f32 v[236:237], v[220:221], v[54:55], v[236:237]
	v_pk_add_f32 v[236:237], v[236:237], v[70:71]
	v_mul_f32_e32 v238, 0xbfb8aa3b, v222
	v_mul_f32_e32 v239, 0xbfb8aa3b, v223
	v_mul_f32_e32 v240, 0xbfb8aa3b, v224
	v_mul_f32_e32 v241, 0xbfb8aa3b, v225
	v_mul_f32_e32 v242, 0xbfb8aa3b, v226
	v_mul_f32_e32 v243, 0xbfb8aa3b, v227
	v_mul_f32_e32 v244, 0xbfb8aa3b, v228
	v_mul_f32_e32 v245, 0xbfb8aa3b, v229
	v_exp_f32_e32 v238, v238
	v_exp_f32_e32 v239, v239
	v_exp_f32_e32 v240, v240
	v_exp_f32_e32 v241, v241
	v_exp_f32_e32 v242, v242
	v_exp_f32_e32 v243, v243
	v_exp_f32_e32 v244, v244
	v_exp_f32_e32 v245, v245
	v_add_f32_e32 v238, 1.0, v238
	v_add_f32_e32 v239, 1.0, v239
	v_add_f32_e32 v240, 1.0, v240
	v_add_f32_e32 v241, 1.0, v241
	v_add_f32_e32 v242, 1.0, v242
	v_add_f32_e32 v243, 1.0, v243
	v_add_f32_e32 v244, 1.0, v244
	v_add_f32_e32 v245, 1.0, v245
	v_rcp_f32_e32 v238, v238
	v_rcp_f32_e32 v239, v239
	v_rcp_f32_e32 v240, v240
	v_rcp_f32_e32 v241, v241
	v_rcp_f32_e32 v242, v242
	v_rcp_f32_e32 v243, v243
	v_rcp_f32_e32 v244, v244
	v_rcp_f32_e32 v245, v245
	v_mul_f32_e32 v238, v222, v238
	v_mul_f32_e32 v239, v223, v239
	v_mul_f32_e32 v240, v224, v240
	v_mul_f32_e32 v241, v225, v241
	v_mul_f32_e32 v242, v226, v242
	v_mul_f32_e32 v243, v227, v243
	v_mul_f32_e32 v244, v228, v244
	v_mul_f32_e32 v245, v229, v245
	v_mul_f32_e32 v238, v238, v230
	v_mul_f32_e32 v239, v239, v231
	v_mul_f32_e32 v240, v240, v232
	v_mul_f32_e32 v241, v241, v233
	v_mul_f32_e32 v242, v242, v234
	v_mul_f32_e32 v243, v243, v235
	v_mul_f32_e32 v244, v244, v236
	v_mul_f32_e32 v245, v245, v237
	v_cvt_pk_bf16_f32 v246, v238, v239
	v_cvt_pk_bf16_f32 v247, v240, v241
	v_cvt_pk_bf16_f32 v248, v242, v243
	v_cvt_pk_bf16_f32 v249, v244, v245
	global_store_dwordx4 v1, v[246:249], s[24:25]
	s_add_u32 s24, s24, 0x2b00
	s_addc_u32 s25, s25, 0
	v_lshlrev_b32_e32 v168, 16, v116
	v_and_b32_e32 v169, 0xffff0000, v116
	v_lshlrev_b32_e32 v170, 16, v117
	v_and_b32_e32 v171, 0xffff0000, v117
	v_lshlrev_b32_e32 v172, 16, v118
	v_and_b32_e32 v173, 0xffff0000, v118
	v_lshlrev_b32_e32 v174, 16, v119
	v_and_b32_e32 v175, 0xffff0000, v119
	v_lshlrev_b32_e32 v192, 16, v132
	v_and_b32_e32 v193, 0xffff0000, v132
	v_lshlrev_b32_e32 v194, 16, v133
	v_and_b32_e32 v195, 0xffff0000, v133
	v_lshlrev_b32_e32 v196, 16, v134
	v_and_b32_e32 v197, 0xffff0000, v134
	v_lshlrev_b32_e32 v198, 16, v135
	v_and_b32_e32 v199, 0xffff0000, v135
	v_pk_mul_f32 v[222:223], v[176:177], v[8:9]
	v_pk_fma_f32 v[222:223], v[184:185], v[16:17], v[222:223]
	v_pk_fma_f32 v[222:223], v[168:169], v[24:25], v[222:223]
	v_pk_add_f32 v[222:223], v[222:223], v[56:57]
	v_pk_mul_f32 v[224:225], v[178:179], v[10:11]
	v_pk_fma_f32 v[224:225], v[186:187], v[18:19], v[224:225]
	v_pk_fma_f32 v[224:225], v[170:171], v[26:27], v[224:225]
	v_pk_add_f32 v[224:225], v[224:225], v[58:59]
; __device__ __forceinline__ float siluf_(float x) { return x * __builtin_amdgcn_rcpf(1.f + __expf(-x)); }
; #define ST8(ptr, src) do { *(f32x4*)(ptr) = (f32x4){src[0], src[1], src[2], src[3]}; *(f32x4*)((ptr) + 4) = (f32x4){src[4], src[5], src[6], src[7]}; } while (0)
; template <int NT, bool SAMPLE>
; __device__ __forceinline__ void ffn_item(const bf16_t* U, int row0, bool has_hist, const float* st, int cgi, const float* w, const float* bias, bf16_t* ACT, float* state_out) {
;     ...
;     for (int t = 0; t < NT; ++t) {
;         float cg_[8], cv_[8], o[8];
;         unpack8(rg[t], cg_); unpack8(rv[t], cv_);
; #pragma unroll
;         for (int e = 0; e < 8; ++e) {
;             const float gg = g0[e] * wg[0][e] + g1[e] * wg[1][e] + cg_[e] * wg[2][e] + bg[e];
;             const float vv = v0[e] * wv[0][e] + v1[e] * wv[1][e] + cv_[e] * wv[2][e] + bvv[e];
;             o[e] = siluf_(gg) * vv; g0[e] = g1[e]; g1[e] = cg_[e]; v0[e] = v1[e]; v1[e] = cv_[e]; }
;         *(u32x4*)(ACT + (size_t)(row0 + t) * FF + c0) = pack8(o);
;     }
;     if (state_out) {
;     ...
;         ST8(state_out + 0 * FF2 + c0, g0); ST8(state_out + 1 * FF2 + c0, g1); ST8(state_out + 0 * FF2 + FF + c0, v0); ST8(state_out + 1 * FF2 + FF + c0, v1);
;     ...
;     }
	v_pk_mul_f32 v[226:227], v[180:181], v[12:13]
	v_pk_fma_f32 v[226:227], v[188:189], v[20:21], v[226:227]
	v_pk_fma_f32 v[226:227], v[172:173], v[28:29], v[226:227]
	v_pk_add_f32 v[226:227], v[226:227], v[60:61]
	v_pk_mul_f32 v[228:229], v[182:183], v[14:15]
	v_pk_fma_f32 v[228:229], v[190:191], v[22:23], v[228:229]
	v_pk_fma_f32 v[228:229], v[174:175], v[30:31], v[228:229]
	v_pk_add_f32 v[228:229], v[228:229], v[62:63]
	v_pk_mul_f32 v[230:231], v[200:201], v[32:33]
	v_pk_fma_f32 v[230:231], v[214:215], v[40:41], v[230:231]
	v_pk_fma_f32 v[230:231], v[192:193], v[48:49], v[230:231]
	v_pk_add_f32 v[230:231], v[230:231], v[64:65]
	v_pk_mul_f32 v[232:233], v[202:203], v[34:35]
	v_pk_fma_f32 v[232:233], v[216:217], v[42:43], v[232:233]
	v_pk_fma_f32 v[232:233], v[194:195], v[50:51], v[232:233]
	v_pk_add_f32 v[232:233], v[232:233], v[66:67]
	v_pk_mul_f32 v[234:235], v[204:205], v[36:37]
	v_pk_fma_f32 v[234:235], v[218:219], v[44:45], v[234:235]
	v_pk_fma_f32 v[234:235], v[196:197], v[52:53], v[234:235]
	v_pk_add_f32 v[234:235], v[234:235], v[68:69]
	v_pk_mul_f32 v[236:237], v[206:207], v[38:39]
	v_pk_fma_f32 v[236:237], v[220:221], v[46:47], v[236:237]
	v_pk_fma_f32 v[236:237], v[198:199], v[54:55], v[236:237]
	v_pk_add_f32 v[236:237], v[236:237], v[70:71]
	v_mul_f32_e32 v238, 0xbfb8aa3b, v222
	v_mul_f32_e32 v239, 0xbfb8aa3b, v223
	v_mul_f32_e32 v240, 0xbfb8aa3b, v224
	v_mul_f32_e32 v241, 0xbfb8aa3b, v225
	v_mul_f32_e32 v242, 0xbfb8aa3b, v226
	v_mul_f32_e32 v243, 0xbfb8aa3b, v227
	v_mul_f32_e32 v244, 0xbfb8aa3b, v228
	v_mul_f32_e32 v245, 0xbfb8aa3b, v229
	v_exp_f32_e32 v238, v238
	v_exp_f32_e32 v239, v239
	v_exp_f32_e32 v240, v240
	v_exp_f32_e32 v241, v241
	v_exp_f32_e32 v242, v242
	v_exp_f32_e32 v243, v243
	v_exp_f32_e32 v244, v244
	v_exp_f32_e32 v245, v245
	v_add_f32_e32 v238, 1.0, v238
	v_add_f32_e32 v239, 1.0, v239
	v_add_f32_e32 v240, 1.0, v240
	v_add_f32_e32 v241, 1.0, v241
	v_add_f32_e32 v242, 1.0, v242
	v_add_f32_e32 v243, 1.0, v243
	v_add_f32_e32 v244, 1.0, v244
	v_add_f32_e32 v245, 1.0, v245
	v_rcp_f32_e32 v238, v238
	v_rcp_f32_e32 v239, v239
	v_rcp_f32_e32 v240, v240
	v_rcp_f32_e32 v241, v241
	v_rcp_f32_e32 v242, v242
	v_rcp_f32_e32 v243, v243
	v_rcp_f32_e32 v244, v244
	v_rcp_f32_e32 v245, v245
	v_mul_f32_e32 v238, v222, v238
	v_mul_f32_e32 v239, v223, v239
	v_mul_f32_e32 v240, v224, v240
	v_mul_f32_e32 v241, v225, v241
	v_mul_f32_e32 v242, v226, v242
	v_mul_f32_e32 v243, v227, v243
	v_mul_f32_e32 v244, v228, v244
	v_mul_f32_e32 v245, v229, v245
	v_mul_f32_e32 v238, v238, v230
	v_mul_f32_e32 v239, v239, v231
	v_mul_f32_e32 v240, v240, v232
	v_mul_f32_e32 v241, v241, v233
	v_mul_f32_e32 v242, v242, v234
	v_mul_f32_e32 v243, v243, v235
	v_mul_f32_e32 v244, v244, v236
	v_mul_f32_e32 v245, v245, v237
	v_cvt_pk_bf16_f32 v246, v238, v239
	v_cvt_pk_bf16_f32 v247, v240, v241
	v_cvt_pk_bf16_f32 v248, v242, v243
	v_cvt_pk_bf16_f32 v249, v244, v245
	global_store_dwordx4 v1, v[246:249], s[24:25]
	s_mul_i32 s5, s33, 0x15800
	s_add_u32 s26, s12, s5
	s_addc_u32 s27, s13, 0
	s_add_u32 s26, s26, 0xebea000
	s_addc_u32 s27, s27, 0
	global_store_dwordx4 v3, v[184:187], s[26:27]
	global_store_dwordx4 v3, v[188:191], s[26:27] offset:16
	global_store_dwordx4 v4, v[214:217], s[26:27]
	global_store_dwordx4 v4, v[218:221], s[26:27] offset:16
	s_add_u32 s26, s26, 0xac00
	s_addc_u32 s27, s27, 0
	global_store_dwordx4 v3, v[168:171], s[26:27]
	global_store_dwordx4 v3, v[172:175], s[26:27] offset:16
	global_store_dwordx4 v4, v[192:195], s[26:27]
	global_store_dwordx4 v4, v[196:199], s[26:27] offset:16
